# SSD states: two units unrolled, unit-2 conv-input loads prefetched during unit 1 (plus earlier epilogue/mask edits)
# speedup vs baseline: 1.0087x; 1.0087x over previous
; #define LAS __attribute__((address_space(3)))
;     __device__ __forceinline__ int tid_() const { return wave * 64 + lane_(); }
; __device__ __forceinline__ void states_unit(Frame& F, const Ptrs& P, int b, int c, int g, int hh) {
;     const bf16* XBC = (const bf16*)(P.ws + WS_XBC); float* DEC = (float*)(P.ws + WS_DEC); unsigned char* SB = (unsigned char*)P.out;
;     int tid = F.tid_(); asm volatile("" : "+v"(tid));
;     const int lane = tid & 63, wid = F.wave, r32 = lane & 31, hi = lane >> 5, h0 = 8 * g + 4 * hh;
;     LAS unsigned char* lds = F.lds;
; __device__ __forceinline__ void states_phase(Frame& F, const Ptrs& P) {
;     for (int u = F.vcu; u < 512; u += F.G) states_unit(F, P, u >> 8, (u >> 2) & 63, (u >> 1) & 1, u & 1);
.LBB0_559:
	s_and_b64 vcc, exec, s[0:1]
	s_cbranch_vccz .LBB0_706
	v_readlane_b32 s0, v252, 4
	s_cmpk_lt_i32 s0, 0x200
	s_cselect_b64 s[8:9], -1, 0
	s_cmpk_gt_i32 s0, 0x1ff
	s_cbranch_scc1 .LBB0_580
	s_add_u32 s10, s96, 0x5c00000
	s_addc_u32 s11, s97, 0
	s_add_u32 s12, s96, 0x40000
	s_addc_u32 s13, s97, 0
	s_add_u32 s33, s96, 0x18000
	v_readlane_b32 s2, v252, 5
	s_addc_u32 s34, s97, 0
	v_readlane_b32 s3, v252, 13
	s_lshl_b32 s0, s2, 6
	s_lshr_b32 s35, s3, 7
	s_and_b32 s0, s0, 64
	s_add_u32 s0, s96, s0
	s_addc_u32 s1, s97, 0
	s_add_u32 s20, s0, 0xfc00000
	s_addc_u32 s21, s1, 0
	s_add_u32 s22, s24, 0x1800
	s_addc_u32 s23, s25, 0
	s_add_u32 s28, s24, 0x3000
	s_addc_u32 s29, s25, 0
	s_bfe_u32 s30, s3, 0x10006
	s_bitcmp1_b32 s3, 6
	s_cselect_b64 s[62:63], -1, 0
	s_cmp_eq_u32 s30, 0
	s_cselect_b32 s69, s37, s39
	s_cselect_b32 s68, s36, s38
	s_lshl_b32 s75, s2, 11
	s_lshl_b32 s0, s35, 14
	s_lshl_b32 s1, s2, 13
	s_mov_b32 s17, 0
	s_add_i32 s61, s75, 0
	s_and_b32 s74, s1, 0x2000
	s_add_i32 s76, s0, 0
	s_mov_b64 s[14:15], 0x40000
	s_add_i32 s61, s61, 0x20000
	s_mov_b32 s31, s17
	s_and_b32 s64, s75, 0x7ffff000
	s_movk_i32 s65, 0x2000
	s_bitset1_b32 s75, 11
	s_add_i32 s76, s76, s74
	v_mov_b32_e32 v129, 0
	v_mov_b32_e32 v132, 0x1fff
	s_movk_i32 s77, 0xc00
	v_mov_b64_e32 v[130:131], s[10:11]
	v_mov_b32_e32 v133, 0xc00
	s_mov_b32 s78, 0x3fb8aa3b
	s_mov_b32 s79, 0xc2ce8ed0
	s_mov_b32 s80, 0x42b17218
	s_mov_b32 s81, 0x800000
	s_add_i32 s82, 0, 0x10000
	v_mov_b32_e32 v134, 0x7f800000
	v_mov_b32_e32 v135, 0x3ffffffe
	v_mov_b32_e32 v136, 0x3ffffffc
	v_mov_b32_e32 v137, 0x3ffffff8
	v_mov_b32_e32 v138, 0x3ffffff0
	v_mov_b32_e32 v139, 0x3fffffe0
	v_mov_b32_e32 v140, 0x42000000
	s_mov_b32 s100, 0x1800000
	s_mov_b32 s101, 0
	v_readlane_b32 s83, v252, 4
; __device__ __forceinline__ void conv_load(ConvRaw& R, const bf16* XBC, int b, int c, int col0, int rg) {
;     const int r0 = 8 * rg;
; #pragma unroll
;     for (int i = 0; i < 10; ++i) { int t = c * 128 + r0 - 1 + i; t = t < 0 ? 0 : (t > SEQ - 1 ? SEQ - 1 : t); R.r[i] = *(const u32x4*)(XBC + ((size_t)b * SEQ + t) * XBCW + col0); }
;     if (c == 0 && rg == 0) R.r[0] = (u32x4){0u, 0u, 0u, 0u};
;     if (c == 63 && rg == 15) R.r[9] = (u32x4){0u, 0u, 0u, 0u};
; }
; __device__ __forceinline__ void states_unit(Frame& F, const Ptrs& P, int b, int c, int g, int hh) {
;     ...
;         ConvRawN<4> Rb; ConvRaw Rx; const int chb = tid & 15, rgb = tid >> 4, hlx = tid >> 7, chx = tid & 7, rgx = (tid >> 3) & 15;
;         conv_load_n<4>(Rb, XBC, b, c, 1024 + g * 128 + 8 * chb, rgb);
;         conv_load(Rx, XBC, b, c, (h0 + hlx) * 64 + 8 * chx, rgx);
;         if (wid == 0 && lane == 0) { const unsigned* fl = (const unsigned*)(P.ws + WS_CTL) + CW_DTF + (b * 128 + 2 * c); unsigned sp = 0u;
;             while ((__hip_atomic_load(fl, __ATOMIC_RELAXED, __HIP_MEMORY_SCOPE_AGENT) & __hip_atomic_load(fl + 1, __ATOMIC_RELAXED, __HIP_MEMORY_SCOPE_AGENT)) == 0u) { __builtin_amdgcn_s_sleep(1); if (++sp > (1u << 22)) break; } }
.LBB0_562:
	s_bfe_u32 s84, s83, 0x60002
	s_bfe_u32 s0, s83, 0x10001
	v_mbcnt_lo_u32_b32 v0, -1, 0
	v_mbcnt_hi_u32_b32 v0, -1, v0
	s_lshl_b32 s2, s83, 2
	v_add_u32_e32 v100, s60, v0
	s_lshl_b32 s1, s0, 3
	s_and_b32 s2, s2, 4
	v_ashrrev_i32_e32 v99, 4, v100
	s_lshl_b32 s85, s84, 7
	s_ashr_i32 s70, s83, 8
	s_or_b32 s16, s1, s2
	v_and_b32_e32 v98, 15, v100
	s_lshl_b32 s0, s0, 7
	v_lshlrev_b32_e32 v2, 2, v99
	s_add_i32 s2, s85, -1
	v_lshl_or_b32 v0, v98, 3, s0
	v_add_u32_e32 v4, s2, v2
	s_ashr_i32 s71, s70, 31
	v_or_b32_e32 v56, 0x400, v0
	s_lshl_b64 s[4:5], s[70:71], 13
	v_med3_i32 v0, v4, 0, v132
	v_add_u32_e32 v2, s85, v2
	v_or_b32_e32 v0, s4, v0
	v_med3_i32 v2, v2, 0, v132
	s_waitcnt lgkmcnt(0)
	v_mad_u64_u32 v[0:1], s[0:1], v0, s77, v[130:131]
	v_or_b32_e32 v2, s4, v2
	v_mad_i32_i24 v1, s5, v133, v1
	v_lshlrev_b32_e32 v128, 1, v56
	v_mad_u64_u32 v[2:3], s[0:1], v2, s77, v[130:131]
	v_lshl_add_u64 v[0:1], v[0:1], 0, v[128:129]
	v_mad_i32_i24 v3, s5, v133, v3
	v_lshl_add_u64 v[2:3], v[2:3], 0, v[128:129]
	v_lshl_add_u64 v[146:147], v[0:1], 0, s[100:101]
	global_load_dwordx4 v[88:91], v[0:1], off
	v_lshl_add_u64 v[148:149], v[2:3], 0, s[100:101]
	global_load_dwordx4 v[48:51], v[2:3], off
	v_max_i32_e32 v0, -2, v4
	v_add_u32_e32 v0, 2, v0
	v_max_i32_e32 v2, -3, v4
	v_min_u32_e32 v0, 0x1fff, v0
	v_add_u32_e32 v2, 3, v2
	v_or_b32_e32 v0, s4, v0
	v_min_u32_e32 v2, 0x1fff, v2
	v_mad_u64_u32 v[0:1], s[0:1], v0, s77, v[130:131]
	v_or_b32_e32 v2, s4, v2
	v_mad_i32_i24 v1, s5, v133, v1
	v_mad_u64_u32 v[2:3], s[0:1], v2, s77, v[130:131]
	v_lshl_add_u64 v[0:1], v[0:1], 0, v[128:129]
	v_mad_i32_i24 v3, s5, v133, v3
	v_lshl_add_u64 v[2:3], v[2:3], 0, v[128:129]
	v_lshl_add_u64 v[150:151], v[0:1], 0, s[100:101]
	global_load_dwordx4 v[52:55], v[0:1], off
	v_lshl_add_u64 v[152:153], v[2:3], 0, s[100:101]
	global_load_dwordx4 v[44:47], v[2:3], off
	v_max_i32_e32 v0, -4, v4
	v_add_u32_e32 v0, 4, v0
	v_max_i32_e32 v2, -5, v4
	v_min_u32_e32 v0, 0x1fff, v0
	v_add_u32_e32 v2, 5, v2
	v_or_b32_e32 v0, s4, v0
	v_min_u32_e32 v2, 0x1fff, v2
	v_mad_u64_u32 v[0:1], s[0:1], v0, s77, v[130:131]
	v_or_b32_e32 v2, s4, v2
	v_mad_i32_i24 v1, s5, v133, v1
	v_mad_u64_u32 v[2:3], s[0:1], v2, s77, v[130:131]
	v_ashrrev_i32_e32 v103, 7, v100
	v_and_b32_e32 v101, 7, v100
	v_bfe_u32 v102, v100, 3, 4
	v_lshl_add_u64 v[0:1], v[0:1], 0, v[128:129]
	v_mad_i32_i24 v3, s5, v133, v3
	v_lshl_add_u64 v[2:3], v[2:3], 0, v[128:129]
	v_lshl_add_u64 v[154:155], v[0:1], 0, s[100:101]
	global_load_dwordx4 v[40:43], v[0:1], off
	v_lshl_add_u64 v[156:157], v[2:3], 0, s[100:101]
	global_load_dwordx4 v[92:95], v[2:3], off
	v_add_u32_e32 v0, s16, v103
	v_lshlrev_b32_e32 v1, 3, v101
	v_lshlrev_b32_e32 v6, 3, v102
	v_lshl_or_b32 v96, v0, 6, v1
	v_add_u32_e32 v38, s2, v6
	v_ashrrev_i32_e32 v97, 31, v96
	v_max_i32_e32 v128, 0, v38
	v_lshl_add_u64 v[0:1], v[96:97], 1, s[10:11]
	v_lshl_add_u64 v[2:3], s[4:5], 0, v[128:129]
	v_mad_u64_u32 v[4:5], s[0:1], v2, s77, v[0:1]
	v_or_b32_e32 v2, s85, v6
	v_or_b32_e32 v2, s4, v2
	v_mad_i32_i24 v5, v3, s77, v5
	v_mad_u64_u32 v[2:3], s[0:1], v2, s77, v[0:1]
	v_mad_i32_i24 v3, s5, v133, v3
	v_add_u32_e32 v128, 2, v38
	v_lshl_add_u64 v[158:159], v[4:5], 0, s[100:101]
	global_load_dwordx4 v[32:35], v[4:5], off
	v_lshl_add_u64 v[160:161], v[2:3], 0, s[100:101]
	global_load_dwordx4 v[24:27], v[2:3], off
	v_lshl_add_u64 v[2:3], s[4:5], 0, v[128:129]
	v_mad_u64_u32 v[4:5], s[0:1], v2, s77, v[0:1]
	v_add_u32_e32 v128, 3, v38
	v_mad_i32_i24 v5, v3, s77, v5
	v_lshl_add_u64 v[2:3], s[4:5], 0, v[128:129]
	v_mad_u64_u32 v[6:7], s[0:1], v2, s77, v[0:1]
	v_add_u32_e32 v128, 4, v38
	v_mad_i32_i24 v7, v3, s77, v7
	v_lshl_add_u64 v[2:3], s[4:5], 0, v[128:129]
	v_lshl_add_u64 v[162:163], v[4:5], 0, s[100:101]
	global_load_dwordx4 v[28:31], v[4:5], off
	v_lshl_add_u64 v[164:165], v[6:7], 0, s[100:101]
	global_load_dwordx4 v[20:23], v[6:7], off
	v_mad_u64_u32 v[4:5], s[0:1], v2, s77, v[0:1]
	v_add_u32_e32 v128, 5, v38
	v_mad_i32_i24 v5, v3, s77, v5
	v_lshl_add_u64 v[2:3], s[4:5], 0, v[128:129]
	v_mad_u64_u32 v[6:7], s[0:1], v2, s77, v[0:1]
	v_add_u32_e32 v128, 6, v38
	v_mad_i32_i24 v7, v3, s77, v7
	v_lshl_add_u64 v[2:3], s[4:5], 0, v[128:129]
	v_lshl_add_u64 v[166:167], v[4:5], 0, s[100:101]
	global_load_dwordx4 v[16:19], v[4:5], off
	v_lshl_add_u64 v[168:169], v[6:7], 0, s[100:101]
	global_load_dwordx4 v[12:15], v[6:7], off
	v_mad_u64_u32 v[4:5], s[0:1], v2, s77, v[0:1]
	v_add_u32_e32 v128, 7, v38
	v_mad_i32_i24 v5, v3, s77, v5
	v_lshl_add_u64 v[2:3], s[4:5], 0, v[128:129]
	v_mad_u64_u32 v[6:7], s[0:1], v2, s77, v[0:1]
	v_add_u32_e32 v128, 8, v38
	v_mad_i32_i24 v7, v3, s77, v7
	v_lshl_add_u64 v[2:3], s[4:5], 0, v[128:129]
	v_mad_u64_u32 v[36:37], s[0:1], v2, s77, v[0:1]
	v_add_u32_e32 v2, 9, v38
	v_min_u32_e32 v2, 0x1fff, v2
	v_or_b32_e32 v2, s4, v2
	v_mad_u64_u32 v[38:39], s[0:1], v2, s77, v[0:1]
	v_mad_i32_i24 v37, v3, s77, v37
	v_mad_i32_i24 v39, s5, v133, v39
	v_lshl_add_u64 v[170:171], v[4:5], 0, s[100:101]
	global_load_dwordx4 v[8:11], v[4:5], off
	s_nop 0
	v_lshl_add_u64 v[172:173], v[6:7], 0, s[100:101]
	global_load_dwordx4 v[4:7], v[6:7], off
	s_nop 0
	v_lshl_add_u64 v[174:175], v[36:37], 0, s[100:101]
	global_load_dwordx4 v[0:3], v[36:37], off
	s_nop 0
	v_lshl_add_u64 v[176:177], v[38:39], 0, s[100:101]
	global_load_dwordx4 v[36:39], v[38:39], off
	v_and_b32_e32 v104, 63, v100
	v_readlane_b32 s0, v252, 5
	s_nop 1
	v_or_b32_e32 v57, s0, v104
	v_cmp_eq_u32_e32 vcc, 0, v57
	s_and_saveexec_b64 s[0:1], vcc
	s_cbranch_execz .LBB0_571
	s_lshl_b32 s2, s70, 7
	s_lshl_b32 s3, s84, 1
	s_or_b32 s2, s3, s2
	s_ashr_i32 s3, s2, 31
	s_lshl_b64 s[2:3], s[2:3], 2
	s_add_u32 s2, s33, s2
	s_addc_u32 s3, s34, s3
	s_mov_b32 s72, 0x400001
	s_branch .LBB0_565

; __device__ __forceinline__ unsigned cvtpk(float lo, float hi) { f32x2_t v = {lo, hi}; bf16x2_t b = __builtin_convertvector(v, bf16x2_t); return __builtin_bit_cast(unsigned, b); }
; __device__ __forceinline__ float lo16(unsigned u) { return __uint_as_float(u << 16); }
; __device__ __forceinline__ float hi16(unsigned u) { return __uint_as_float(u & 0xffff0000u); }
; __device__ __forceinline__ float silu_fast(float v) { return v * __builtin_amdgcn_rcpf(1.f + __builtin_amdgcn_exp2f(-v * LOG2E)); }
; __device__ __forceinline__ unsigned cvtpk(float lo, float hi) { f32x2_t v = {lo, hi}; bf16x2_t b = __builtin_convertvector(v, bf16x2_t); return __builtin_bit_cast(unsigned, b); }
; template <class Put>
; __device__ __forceinline__ void conv_compute(const ConvRaw& R, const float* cw, const float* cb, int col0, int rg, const Put& put) {
;     const f32x4 w0a = *(const f32x4*)(cw + col0), w0b = *(const f32x4*)(cw + col0 + 4), w1a = *(const f32x4*)(cw + XBCW + col0), w1b = *(const f32x4*)(cw + XBCW + col0 + 4);
;     const f32x4 w2a = *(const f32x4*)(cw + 2 * XBCW + col0), w2b = *(const f32x4*)(cw + 2 * XBCW + col0 + 4), ba = *(const f32x4*)(cb + col0), bb = *(const f32x4*)(cb + col0 + 4);
;     const int r0 = 8 * rg;
; #pragma unroll
;     for (int rr = 0; rr < 8; ++rr) {
;         const u32x4 xm = R.r[rr], x0 = R.r[rr + 1], xp = R.r[rr + 2]; u32x4 o;
; #pragma unroll
;         for (int e = 0; e < 4; ++e) {
;             const float wl0 = e < 2 ? w0a[2 * e] : w0b[2 * e - 4], wh0 = e < 2 ? w0a[2 * e + 1] : w0b[2 * e - 3];
;             const float wl1 = e < 2 ? w1a[2 * e] : w1b[2 * e - 4], wh1 = e < 2 ? w1a[2 * e + 1] : w1b[2 * e - 3];
;             const float wl2 = e < 2 ? w2a[2 * e] : w2b[2 * e - 4], wh2 = e < 2 ? w2a[2 * e + 1] : w2b[2 * e - 3];
;             const float bl = e < 2 ? ba[2 * e] : bb[2 * e - 4], bh = e < 2 ? ba[2 * e + 1] : bb[2 * e - 3];
;             const float vl = bl + wl0 * lo16(xm[e]) + wl1 * lo16(x0[e]) + wl2 * lo16(xp[e]);
;             const float vh = bh + wh0 * hi16(xm[e]) + wh1 * hi16(x0[e]) + wh2 * hi16(xp[e]);
;             o[e] = cvtpk(silu_fast(vl), silu_fast(vh));
;         }
;         put(r0 + rr, o);
;     }
; }
; __device__ __forceinline__ void states_unit(Frame& F, const Ptrs& P, int b, int c, int g, int hh) {
;     ...
;         conv_compute(Rx, P.conv_w, P.conv_b, (h0 + hlx) * 64 + 8 * chx, rgx, PutTr{lds + L_XS + hlx * 16384, chx});
.LBB0_577:
	s_or_b64 exec, exec, s[0:1]
	v_lshlrev_b64 v[44:45], 2, v[96:97]
	v_lshl_add_u64 v[46:47], s[24:25], 0, v[44:45]
	global_load_dwordx4 v[40:43], v[46:47], off offset:16
	global_load_dwordx4 v[56:59], v[46:47], off
	v_lshl_add_u64 v[46:47], s[26:27], 0, v[44:45]
	global_load_dwordx4 v[60:63], v[46:47], off
	global_load_dwordx4 v[48:51], v[46:47], off offset:16
	v_lshl_add_u64 v[46:47], s[22:23], 0, v[44:45]
	global_load_dwordx4 v[64:67], v[46:47], off
	global_load_dwordx4 v[52:55], v[46:47], off offset:16
	v_lshl_add_u64 v[44:45], s[28:29], 0, v[44:45]
	global_load_dwordx4 v[68:71], v[44:45], off
	s_nop 0
	global_load_dwordx4 v[44:47], v[44:45], off offset:16
	global_load_dwordx4 v[188:191], v[146:147], off
	global_load_dwordx4 v[192:195], v[148:149], off
	global_load_dwordx4 v[196:199], v[150:151], off
	global_load_dwordx4 v[200:203], v[152:153], off
	global_load_dwordx4 v[204:207], v[154:155], off
	global_load_dwordx4 v[208:211], v[156:157], off
	global_load_dwordx4 v[212:215], v[158:159], off
	global_load_dwordx4 v[216:219], v[160:161], off
	global_load_dwordx4 v[220:223], v[162:163], off
	global_load_dwordx4 v[224:227], v[164:165], off
	global_load_dwordx4 v[228:231], v[166:167], off
	global_load_dwordx4 v[232:235], v[168:169], off
	global_load_dwordx4 v[236:239], v[170:171], off
	global_load_dwordx4 v[240:243], v[172:173], off
	global_load_dwordx4 v[244:247], v[174:175], off
	global_load_dwordx4 v[248:251], v[176:177], off
	v_or_b32_e32 v80, s84, v102
	v_cmp_eq_u32_e32 vcc, 15, v102
	v_lshlrev_b32_e32 v82, 1, v101
	v_lshrrev_b32_e32 v83, 1, v102
	v_cmp_ne_u32_e64 s[0:1], 0, v80
	v_lshlrev_b32_e32 v74, 16, v24
	v_and_b32_e32 v75, 0xffff0000, v24
	v_lshlrev_b32_e32 v72, 16, v28
	v_and_b32_e32 v73, 0xffff0000, v28
	v_lshlrev_b32_e32 v76, 16, v25
	v_and_b32_e32 v77, 0xffff0000, v25
	v_lshlrev_b32_e32 v24, 16, v29
	v_and_b32_e32 v25, 0xffff0000, v29
	v_lshlrev_b32_e32 v28, 16, v30
	v_and_b32_e32 v29, 0xffff0000, v30
	v_cndmask_b32_e64 v30, 0, v35, s[0:1]
	s_and_b64 s[4:5], s[72:73], vcc
	v_and_or_b32 v35, v82, 8, v83
	v_lshlrev_b32_e32 v81, 14, v103
	v_lshlrev_b32_e32 v78, 16, v26
	v_and_b32_e32 v79, 0xffff0000, v26
	v_cndmask_b32_e64 v26, v39, 0, s[4:5]
	v_cndmask_b32_e64 v83, 0, v34, s[0:1]
	v_cndmask_b32_e64 v82, 0, v33, s[0:1]
	v_cndmask_b32_e64 v39, 0, v32, s[0:1]
	v_lshlrev_b32_e32 v35, 10, v35
	v_cndmask_b32_e64 v32, v38, 0, s[4:5]
	v_cndmask_b32_e64 v33, v37, 0, s[4:5]
	v_cndmask_b32_e64 v34, v36, 0, s[4:5]
	v_lshlrev_b32_e32 v36, 16, v30
	v_and_b32_e32 v37, 0xffff0000, v30
	v_add3_u32 v30, s82, v81, v35
	v_lshlrev_b32_e32 v38, 16, v39
	v_and_b32_e32 v39, 0xffff0000, v39
	v_lshlrev_b32_e32 v80, 16, v82
	v_and_b32_e32 v81, 0xffff0000, v82
	v_lshlrev_b32_e32 v82, 16, v83
	v_and_b32_e32 v83, 0xffff0000, v83
	v_lshlrev_b32_e32 v84, 9, v102
	v_lshlrev_b32_e32 v85, 4, v101
	v_and_b32_e32 v84, 0x200, v84
	v_and_b32_e32 v85, 48, v85
	v_add3_u32 v30, v30, v84, v85
	v_lshrrev_b32_e32 v128, 5, v104
	v_lshlrev_b32_e32 v141, 4, v100
	s_mov_b32 s2, 0
	v_lshl_add_u32 v142, v128, 4, 0
	s_waitcnt vmcnt(21)
	v_pk_fma_f32 v[38:39], v[56:57], v[38:39], v[60:61]
	v_pk_fma_f32 v[80:81], v[58:59], v[80:81], v[62:63]
	s_waitcnt vmcnt(20)
	v_pk_fma_f32 v[82:83], v[40:41], v[82:83], v[48:49]
	s_waitcnt vmcnt(19)
	v_pk_fma_f32 v[38:39], v[64:65], v[74:75], v[38:39]
	v_pk_fma_f32 v[80:81], v[66:67], v[76:77], v[80:81]
	s_waitcnt vmcnt(18)
	v_pk_fma_f32 v[82:83], v[52:53], v[78:79], v[82:83]
	s_waitcnt vmcnt(17)
	v_pk_fma_f32 v[38:39], v[68:69], v[72:73], v[38:39]
	v_pk_fma_f32 v[80:81], v[70:71], v[24:25], v[80:81]
	s_waitcnt vmcnt(16)
	v_pk_fma_f32 v[82:83], v[44:45], v[28:29], v[82:83]
	v_mul_f32_e32 v35, 0xbfb8aa3b, v38
	v_mul_f32_e32 v84, 0xbfb8aa3b, v39
	v_mul_f32_e32 v85, 0xbfb8aa3b, v80
	v_mul_f32_e32 v86, 0xbfb8aa3b, v81
	v_mul_f32_e32 v87, 0xbfb8aa3b, v82
	v_mul_f32_e32 v88, 0xbfb8aa3b, v83
	v_exp_f32_e32 v35, v35
	v_exp_f32_e32 v84, v84
	v_exp_f32_e32 v85, v85
	v_exp_f32_e32 v86, v86
	v_exp_f32_e32 v87, v87
	v_exp_f32_e32 v88, v88
	v_add_f32_e32 v35, 1.0, v35
	v_add_f32_e32 v89, 1.0, v84
	v_add_f32_e32 v90, 1.0, v85
	v_add_f32_e32 v91, 1.0, v86
	v_add_f32_e32 v92, 1.0, v87
	v_add_f32_e32 v93, 1.0, v88
	v_rcp_f32_e32 v84, v35
	v_rcp_f32_e32 v85, v89
	v_rcp_f32_e32 v86, v90
	v_rcp_f32_e32 v87, v91
	v_rcp_f32_e32 v88, v92
	v_rcp_f32_e32 v89, v93
	v_pk_fma_f32 v[90:91], v[42:43], v[36:37], v[50:51]
	v_pk_mul_f32 v[36:37], v[38:39], v[84:85]
	v_pk_mul_f32 v[38:39], v[80:81], v[86:87]
	v_pk_mul_f32 v[80:81], v[82:83], v[88:89]
	v_lshlrev_b32_e32 v82, 16, v27
	v_and_b32_e32 v83, 0xffff0000, v27
	v_cvt_pk_bf16_f32 v36, v36, v37
	v_cvt_pk_bf16_f32 v37, v38, v39
	v_pk_fma_f32 v[38:39], v[54:55], v[82:83], v[90:91]
	v_lshlrev_b32_e32 v84, 16, v31
	v_and_b32_e32 v85, 0xffff0000, v31
	v_pk_fma_f32 v[86:87], v[46:47], v[84:85], v[38:39]
	v_pk_fma_f32 v[74:75], v[56:57], v[74:75], v[60:61]
	v_mul_f32_e32 v27, 0xbfb8aa3b, v86
	v_exp_f32_e32 v27, v27
	v_mul_f32_e32 v31, 0xbfb8aa3b, v87
	v_exp_f32_e32 v31, v31
	v_pk_fma_f32 v[74:75], v[64:65], v[72:73], v[74:75]
	v_lshlrev_b32_e32 v88, 16, v20
	v_and_b32_e32 v89, 0xffff0000, v20
	v_pk_fma_f32 v[74:75], v[68:69], v[88:89], v[74:75]
	v_add_f32_e32 v27, 1.0, v27
	v_mul_f32_e32 v20, 0xbfb8aa3b, v74
	v_cvt_pk_bf16_f32 v38, v80, v81
	v_rcp_f32_e32 v80, v27
	v_add_f32_e32 v27, 1.0, v31
	v_exp_f32_e32 v20, v20
	v_mul_f32_e32 v31, 0xbfb8aa3b, v75
	v_exp_f32_e32 v31, v31
	v_rcp_f32_e32 v81, v27
	v_add_f32_e32 v20, 1.0, v20
	v_rcp_f32_e32 v90, v20
	v_add_f32_e32 v20, 1.0, v31
	v_rcp_f32_e32 v91, v20
	v_pk_mul_f32 v[80:81], v[86:87], v[80:81]
	s_nop 0
	v_cvt_pk_bf16_f32 v39, v80, v81
	ds_write_b128 v30, v[36:39]
; __device__ __forceinline__ unsigned cvtpk(float lo, float hi) { f32x2_t v = {lo, hi}; bf16x2_t b = __builtin_convertvector(v, bf16x2_t); return __builtin_bit_cast(unsigned, b); }
; __device__ __forceinline__ float lo16(unsigned u) { return __uint_as_float(u << 16); }
; __device__ __forceinline__ float hi16(unsigned u) { return __uint_as_float(u & 0xffff0000u); }
; __device__ __forceinline__ float silu_fast(float v) { return v * __builtin_amdgcn_rcpf(1.f + __builtin_amdgcn_exp2f(-v * LOG2E)); }
; __device__ __forceinline__ unsigned cvtpk(float lo, float hi) { f32x2_t v = {lo, hi}; bf16x2_t b = __builtin_convertvector(v, bf16x2_t); return __builtin_bit_cast(unsigned, b); }
; __device__ __forceinline__ float lo16(unsigned u) { return __uint_as_float(u << 16); }
; __device__ __forceinline__ float hi16(unsigned u) { return __uint_as_float(u & 0xffff0000u); }
; template <class Put>
; __device__ __forceinline__ void conv_compute(const ConvRaw& R, const float* cw, const float* cb, int col0, int rg, const Put& put) {
;     const f32x4 w0a = *(const f32x4*)(cw + col0), w0b = *(const f32x4*)(cw + col0 + 4), w1a = *(const f32x4*)(cw + XBCW + col0), w1b = *(const f32x4*)(cw + XBCW + col0 + 4);
;     const f32x4 w2a = *(const f32x4*)(cw + 2 * XBCW + col0), w2b = *(const f32x4*)(cw + 2 * XBCW + col0 + 4), ba = *(const f32x4*)(cb + col0), bb = *(const f32x4*)(cb + col0 + 4);
;     const int r0 = 8 * rg;
; #pragma unroll
;     for (int rr = 0; rr < 8; ++rr) {
;         const u32x4 xm = R.r[rr], x0 = R.r[rr + 1], xp = R.r[rr + 2]; u32x4 o;
; #pragma unroll
;         for (int e = 0; e < 4; ++e) {
;             const float wl0 = e < 2 ? w0a[2 * e] : w0b[2 * e - 4], wh0 = e < 2 ? w0a[2 * e + 1] : w0b[2 * e - 3];
;             const float wl1 = e < 2 ? w1a[2 * e] : w1b[2 * e - 4], wh1 = e < 2 ? w1a[2 * e + 1] : w1b[2 * e - 3];
;             const float wl2 = e < 2 ? w2a[2 * e] : w2b[2 * e - 4], wh2 = e < 2 ? w2a[2 * e + 1] : w2b[2 * e - 3];
;             const float bl = e < 2 ? ba[2 * e] : bb[2 * e - 4], bh = e < 2 ? ba[2 * e + 1] : bb[2 * e - 3];
;             const float vl = bl + wl0 * lo16(xm[e]) + wl1 * lo16(x0[e]) + wl2 * lo16(xp[e]);
;             const float vh = bh + wh0 * hi16(xm[e]) + wh1 * hi16(x0[e]) + wh2 * hi16(xp[e]);
;             o[e] = cvtpk(silu_fast(vl), silu_fast(vh));
;         }
;         put(r0 + rr, o);
;     }
; }
	v_pk_fma_f32 v[38:39], v[58:59], v[76:77], v[62:63]
	v_pk_mul_f32 v[36:37], v[74:75], v[90:91]
	v_pk_fma_f32 v[38:39], v[66:67], v[24:25], v[38:39]
	v_lshlrev_b32_e32 v74, 16, v21
	v_and_b32_e32 v75, 0xffff0000, v21
	v_pk_fma_f32 v[38:39], v[70:71], v[74:75], v[38:39]
	v_pk_fma_f32 v[76:77], v[40:41], v[78:79], v[48:49]
	v_mul_f32_e32 v20, 0xbfb8aa3b, v38
	v_exp_f32_e32 v21, v20
	v_mul_f32_e32 v20, 0xbfb8aa3b, v39
	v_exp_f32_e32 v27, v20
	v_cvt_pk_bf16_f32 v20, v36, v37
	v_add_f32_e32 v21, 1.0, v21
	v_rcp_f32_e32 v36, v21
	v_add_f32_e32 v21, 1.0, v27
	v_rcp_f32_e32 v37, v21
	v_pk_fma_f32 v[76:77], v[52:53], v[28:29], v[76:77]
	v_lshlrev_b32_e32 v78, 16, v22
	v_and_b32_e32 v79, 0xffff0000, v22
	v_pk_fma_f32 v[76:77], v[44:45], v[78:79], v[76:77]
	v_pk_mul_f32 v[36:37], v[38:39], v[36:37]
	v_mul_f32_e32 v21, 0xbfb8aa3b, v76
	v_exp_f32_e32 v21, v21
	v_mul_f32_e32 v22, 0xbfb8aa3b, v77
	v_exp_f32_e32 v27, v22
	v_pk_fma_f32 v[38:39], v[42:43], v[82:83], v[50:51]
	v_lshlrev_b32_e32 v80, 16, v23
	v_pk_fma_f32 v[38:39], v[54:55], v[84:85], v[38:39]
	v_and_b32_e32 v81, 0xffff0000, v23
	v_pk_fma_f32 v[38:39], v[46:47], v[80:81], v[38:39]
	v_add_f32_e32 v21, 1.0, v21
	v_mul_f32_e32 v23, 0xbfb8aa3b, v38
	v_rcp_f32_e32 v22, v21
	v_add_f32_e32 v21, 1.0, v27
	v_exp_f32_e32 v27, v23
	v_mul_f32_e32 v23, 0xbfb8aa3b, v39
	v_exp_f32_e32 v31, v23
	v_rcp_f32_e32 v23, v21
	v_add_f32_e32 v21, 1.0, v27
	v_rcp_f32_e32 v82, v21
	v_add_f32_e32 v21, 1.0, v31
	v_rcp_f32_e32 v83, v21
	v_cvt_pk_bf16_f32 v21, v36, v37
	v_pk_mul_f32 v[22:23], v[76:77], v[22:23]
	v_pk_fma_f32 v[28:29], v[40:41], v[28:29], v[48:49]
	v_pk_mul_f32 v[36:37], v[38:39], v[82:83]
	v_cvt_pk_bf16_f32 v22, v22, v23
	v_cvt_pk_bf16_f32 v23, v36, v37
	v_pk_fma_f32 v[36:37], v[56:57], v[72:73], v[60:61]
	v_lshlrev_b32_e32 v38, 16, v16
	v_pk_fma_f32 v[36:37], v[64:65], v[88:89], v[36:37]
	v_and_b32_e32 v39, 0xffff0000, v16
	v_pk_fma_f32 v[36:37], v[68:69], v[38:39], v[36:37]
	ds_write_b128 v30, v[20:23] offset:64
	v_mul_f32_e32 v16, 0xbfb8aa3b, v36
	v_exp_f32_e32 v16, v16
	v_mul_f32_e32 v27, 0xbfb8aa3b, v37
	v_exp_f32_e32 v27, v27
	v_pk_fma_f32 v[22:23], v[58:59], v[24:25], v[62:63]
	v_add_f32_e32 v16, 1.0, v16
	v_rcp_f32_e32 v20, v16
	v_add_f32_e32 v16, 1.0, v27
	v_rcp_f32_e32 v21, v16
	v_pk_fma_f32 v[22:23], v[66:67], v[74:75], v[22:23]
	v_lshlrev_b32_e32 v24, 16, v17
	v_and_b32_e32 v25, 0xffff0000, v17
	v_pk_fma_f32 v[22:23], v[70:71], v[24:25], v[22:23]
	v_pk_fma_f32 v[28:29], v[52:53], v[78:79], v[28:29]
	v_mul_f32_e32 v16, 0xbfb8aa3b, v22
	v_exp_f32_e32 v27, v16
	v_mul_f32_e32 v16, 0xbfb8aa3b, v23
	v_exp_f32_e32 v31, v16
	v_pk_mul_f32 v[16:17], v[36:37], v[20:21]
	v_lshlrev_b32_e32 v36, 16, v18
	v_and_b32_e32 v37, 0xffff0000, v18
	v_pk_fma_f32 v[28:29], v[44:45], v[36:37], v[28:29]
	v_add_f32_e32 v20, 1.0, v27
	v_mul_f32_e32 v18, 0xbfb8aa3b, v28
	v_exp_f32_e32 v18, v18
	v_mul_f32_e32 v27, 0xbfb8aa3b, v29
	v_exp_f32_e32 v27, v27
	v_add_f32_e32 v21, 1.0, v31
	v_add_f32_e32 v18, 1.0, v18
	v_rcp_f32_e32 v20, v20
	v_rcp_f32_e32 v21, v21
	v_rcp_f32_e32 v72, v18
	v_add_f32_e32 v18, 1.0, v27
	v_rcp_f32_e32 v73, v18
	v_pk_mul_f32 v[20:21], v[22:23], v[20:21]
	v_pk_fma_f32 v[22:23], v[42:43], v[84:85], v[50:51]
	v_cvt_pk_bf16_f32 v16, v16, v17
	v_cvt_pk_bf16_f32 v17, v20, v21
	v_pk_mul_f32 v[20:21], v[28:29], v[72:73]
	v_pk_fma_f32 v[22:23], v[54:55], v[80:81], v[22:23]
	v_lshlrev_b32_e32 v28, 16, v19
	v_and_b32_e32 v29, 0xffff0000, v19
	v_pk_fma_f32 v[22:23], v[46:47], v[28:29], v[22:23]
	v_pk_fma_f32 v[72:73], v[56:57], v[88:89], v[60:61]
	v_mul_f32_e32 v18, 0xbfb8aa3b, v22
	v_exp_f32_e32 v19, v18
	v_mul_f32_e32 v18, 0xbfb8aa3b, v23
	v_exp_f32_e32 v27, v18
	v_pk_fma_f32 v[72:73], v[64:65], v[38:39], v[72:73]
	v_lshlrev_b32_e32 v76, 16, v12
	v_and_b32_e32 v77, 0xffff0000, v12
	v_add_f32_e32 v19, 1.0, v19
	v_pk_fma_f32 v[72:73], v[68:69], v[76:77], v[72:73]
	v_cvt_pk_bf16_f32 v18, v20, v21
	v_rcp_f32_e32 v20, v19
	v_add_f32_e32 v19, 1.0, v27
	v_mul_f32_e32 v21, 0xbfb8aa3b, v73
	v_exp_f32_e32 v27, v21
	v_rcp_f32_e32 v21, v19
	v_mul_f32_e32 v12, 0xbfb8aa3b, v72
	v_exp_f32_e32 v12, v12
	v_pk_mul_f32 v[20:21], v[22:23], v[20:21]
	s_nop 0
	v_cvt_pk_bf16_f32 v19, v20, v21
	ds_write_b128 v30, v[16:19] offset:128
	v_pk_fma_f32 v[18:19], v[58:59], v[74:75], v[62:63]
	v_add_f32_e32 v12, 1.0, v12
	v_pk_fma_f32 v[18:19], v[66:67], v[24:25], v[18:19]
	v_lshlrev_b32_e32 v20, 16, v13
	v_and_b32_e32 v21, 0xffff0000, v13
	v_rcp_f32_e32 v82, v12
	v_add_f32_e32 v12, 1.0, v27
	v_pk_fma_f32 v[18:19], v[70:71], v[20:21], v[18:19]
	v_rcp_f32_e32 v83, v12
	v_mul_f32_e32 v12, 0xbfb8aa3b, v18
	v_exp_f32_e32 v13, v12
	v_mul_f32_e32 v12, 0xbfb8aa3b, v19
	v_exp_f32_e32 v22, v12
	v_pk_mul_f32 v[16:17], v[72:73], v[82:83]
	v_add_f32_e32 v13, 1.0, v13
	v_cvt_pk_bf16_f32 v12, v16, v17
	v_rcp_f32_e32 v16, v13
	v_add_f32_e32 v13, 1.0, v22
	v_pk_fma_f32 v[22:23], v[40:41], v[78:79], v[48:49]
	v_rcp_f32_e32 v17, v13
	v_pk_fma_f32 v[22:23], v[52:53], v[36:37], v[22:23]
	v_lshlrev_b32_e32 v72, 16, v14
	v_and_b32_e32 v73, 0xffff0000, v14
	v_pk_fma_f32 v[22:23], v[44:45], v[72:73], v[22:23]
	v_pk_mul_f32 v[16:17], v[18:19], v[16:17]
	v_mul_f32_e32 v13, 0xbfb8aa3b, v22
	v_exp_f32_e32 v13, v13
	v_mul_f32_e32 v14, 0xbfb8aa3b, v23
	v_exp_f32_e32 v27, v14
	v_pk_fma_f32 v[18:19], v[42:43], v[80:81], v[50:51]
	v_lshlrev_b32_e32 v74, 16, v15
	v_pk_fma_f32 v[18:19], v[54:55], v[28:29], v[18:19]
	v_and_b32_e32 v75, 0xffff0000, v15
	v_pk_fma_f32 v[18:19], v[46:47], v[74:75], v[18:19]
	v_add_f32_e32 v13, 1.0, v13
	v_mul_f32_e32 v15, 0xbfb8aa3b, v18
	v_rcp_f32_e32 v14, v13
	v_add_f32_e32 v13, 1.0, v27
	v_exp_f32_e32 v27, v15
	v_mul_f32_e32 v15, 0xbfb8aa3b, v19
; __device__ __forceinline__ unsigned cvtpk(float lo, float hi) { f32x2_t v = {lo, hi}; bf16x2_t b = __builtin_convertvector(v, bf16x2_t); return __builtin_bit_cast(unsigned, b); }
; __device__ __forceinline__ float lo16(unsigned u) { return __uint_as_float(u << 16); }
; __device__ __forceinline__ float hi16(unsigned u) { return __uint_as_float(u & 0xffff0000u); }
; __device__ __forceinline__ float silu_fast(float v) { return v * __builtin_amdgcn_rcpf(1.f + __builtin_amdgcn_exp2f(-v * LOG2E)); }
; __device__ __forceinline__ unsigned cvtpk(float lo, float hi) { f32x2_t v = {lo, hi}; bf16x2_t b = __builtin_convertvector(v, bf16x2_t); return __builtin_bit_cast(unsigned, b); }
; __device__ __forceinline__ float lo16(unsigned u) { return __uint_as_float(u << 16); }
; __device__ __forceinline__ float hi16(unsigned u) { return __uint_as_float(u & 0xffff0000u); }
; template <class Put>
; __device__ __forceinline__ void conv_compute(const ConvRaw& R, const float* cw, const float* cb, int col0, int rg, const Put& put) {
;     const f32x4 w0a = *(const f32x4*)(cw + col0), w0b = *(const f32x4*)(cw + col0 + 4), w1a = *(const f32x4*)(cw + XBCW + col0), w1b = *(const f32x4*)(cw + XBCW + col0 + 4);
;     const f32x4 w2a = *(const f32x4*)(cw + 2 * XBCW + col0), w2b = *(const f32x4*)(cw + 2 * XBCW + col0 + 4), ba = *(const f32x4*)(cb + col0), bb = *(const f32x4*)(cb + col0 + 4);
;     const int r0 = 8 * rg;
; #pragma unroll
;     for (int rr = 0; rr < 8; ++rr) {
;         const u32x4 xm = R.r[rr], x0 = R.r[rr + 1], xp = R.r[rr + 2]; u32x4 o;
; #pragma unroll
;         for (int e = 0; e < 4; ++e) {
;             const float wl0 = e < 2 ? w0a[2 * e] : w0b[2 * e - 4], wh0 = e < 2 ? w0a[2 * e + 1] : w0b[2 * e - 3];
;             const float wl1 = e < 2 ? w1a[2 * e] : w1b[2 * e - 4], wh1 = e < 2 ? w1a[2 * e + 1] : w1b[2 * e - 3];
;             const float wl2 = e < 2 ? w2a[2 * e] : w2b[2 * e - 4], wh2 = e < 2 ? w2a[2 * e + 1] : w2b[2 * e - 3];
;             const float bl = e < 2 ? ba[2 * e] : bb[2 * e - 4], bh = e < 2 ? ba[2 * e + 1] : bb[2 * e - 3];
;             const float vl = bl + wl0 * lo16(xm[e]) + wl1 * lo16(x0[e]) + wl2 * lo16(xp[e]);
;             const float vh = bh + wh0 * hi16(xm[e]) + wh1 * hi16(x0[e]) + wh2 * hi16(xp[e]);
;             o[e] = cvtpk(silu_fast(vl), silu_fast(vh));
;         }
;         put(r0 + rr, o);
;     }
; }
	v_exp_f32_e32 v31, v15
	v_rcp_f32_e32 v15, v13
	v_add_f32_e32 v13, 1.0, v27
	v_rcp_f32_e32 v78, v13
	v_add_f32_e32 v13, 1.0, v31
	v_rcp_f32_e32 v79, v13
	v_cvt_pk_bf16_f32 v13, v16, v17
	v_pk_mul_f32 v[14:15], v[22:23], v[14:15]
	v_and_b32_e32 v23, 0xffff0000, v9
	v_pk_mul_f32 v[16:17], v[18:19], v[78:79]
	v_cvt_pk_bf16_f32 v14, v14, v15
	v_cvt_pk_bf16_f32 v15, v16, v17
	v_pk_fma_f32 v[16:17], v[56:57], v[38:39], v[60:61]
	v_lshlrev_b32_e32 v18, 16, v8
	v_pk_fma_f32 v[16:17], v[64:65], v[76:77], v[16:17]
	v_and_b32_e32 v19, 0xffff0000, v8
	v_pk_fma_f32 v[16:17], v[68:69], v[18:19], v[16:17]
	ds_write_b128 v30, v[12:15] offset:192
	v_mul_f32_e32 v8, 0xbfb8aa3b, v16
	v_exp_f32_e32 v8, v8
	v_mul_f32_e32 v22, 0xbfb8aa3b, v17
	v_exp_f32_e32 v22, v22
	v_pk_fma_f32 v[14:15], v[58:59], v[24:25], v[62:63]
	v_add_f32_e32 v8, 1.0, v8
	v_rcp_f32_e32 v12, v8
	v_add_f32_e32 v8, 1.0, v22
	v_pk_fma_f32 v[14:15], v[66:67], v[20:21], v[14:15]
	v_lshlrev_b32_e32 v22, 16, v9
	v_pk_fma_f32 v[14:15], v[70:71], v[22:23], v[14:15]
	v_rcp_f32_e32 v13, v8
	v_mul_f32_e32 v8, 0xbfb8aa3b, v14
	v_exp_f32_e32 v24, v8
	v_mul_f32_e32 v8, 0xbfb8aa3b, v15
	v_exp_f32_e32 v25, v8
	v_pk_mul_f32 v[8:9], v[16:17], v[12:13]
	v_pk_fma_f32 v[16:17], v[40:41], v[36:37], v[48:49]
	v_add_f32_e32 v12, 1.0, v24
	v_add_f32_e32 v13, 1.0, v25
	v_pk_fma_f32 v[16:17], v[52:53], v[72:73], v[16:17]
	v_lshlrev_b32_e32 v24, 16, v10
	v_and_b32_e32 v25, 0xffff0000, v10
	v_pk_fma_f32 v[16:17], v[44:45], v[24:25], v[16:17]
	v_rcp_f32_e32 v12, v12
	v_mul_f32_e32 v10, 0xbfb8aa3b, v16
	v_exp_f32_e32 v10, v10
	v_mul_f32_e32 v27, 0xbfb8aa3b, v17
	v_exp_f32_e32 v27, v27
	v_rcp_f32_e32 v13, v13
	v_add_f32_e32 v10, 1.0, v10
	v_rcp_f32_e32 v36, v10
	v_add_f32_e32 v10, 1.0, v27
	v_rcp_f32_e32 v37, v10
	v_pk_mul_f32 v[12:13], v[14:15], v[12:13]
	v_pk_fma_f32 v[14:15], v[42:43], v[28:29], v[50:51]
	v_cvt_pk_bf16_f32 v8, v8, v9
	v_cvt_pk_bf16_f32 v9, v12, v13
	v_pk_mul_f32 v[12:13], v[16:17], v[36:37]
	v_pk_fma_f32 v[14:15], v[54:55], v[74:75], v[14:15]
	v_lshlrev_b32_e32 v16, 16, v11
	v_and_b32_e32 v17, 0xffff0000, v11
	v_pk_fma_f32 v[14:15], v[46:47], v[16:17], v[14:15]
	v_pk_fma_f32 v[28:29], v[56:57], v[76:77], v[60:61]
	v_mul_f32_e32 v10, 0xbfb8aa3b, v14
	v_exp_f32_e32 v11, v10
	v_mul_f32_e32 v10, 0xbfb8aa3b, v15
	v_exp_f32_e32 v27, v10
	v_pk_fma_f32 v[28:29], v[64:65], v[18:19], v[28:29]
	v_lshlrev_b32_e32 v36, 16, v4
	v_and_b32_e32 v37, 0xffff0000, v4
	v_add_f32_e32 v11, 1.0, v11
	v_pk_fma_f32 v[28:29], v[68:69], v[36:37], v[28:29]
	v_cvt_pk_bf16_f32 v10, v12, v13
	v_rcp_f32_e32 v12, v11
	v_add_f32_e32 v11, 1.0, v27
	v_mul_f32_e32 v13, 0xbfb8aa3b, v29
	v_exp_f32_e32 v27, v13
	v_rcp_f32_e32 v13, v11
	v_mul_f32_e32 v4, 0xbfb8aa3b, v28
	v_exp_f32_e32 v4, v4
	v_pk_mul_f32 v[12:13], v[14:15], v[12:13]
	s_nop 0
	v_cvt_pk_bf16_f32 v11, v12, v13
	ds_write_b128 v30, v[8:11] offset:256
	v_pk_fma_f32 v[10:11], v[58:59], v[20:21], v[62:63]
	v_add_f32_e32 v4, 1.0, v4
	v_pk_fma_f32 v[10:11], v[66:67], v[22:23], v[10:11]
	v_lshlrev_b32_e32 v12, 16, v5
	v_and_b32_e32 v13, 0xffff0000, v5
	v_rcp_f32_e32 v38, v4
	v_add_f32_e32 v4, 1.0, v27
	v_pk_fma_f32 v[10:11], v[70:71], v[12:13], v[10:11]
	v_rcp_f32_e32 v39, v4
	v_mul_f32_e32 v4, 0xbfb8aa3b, v10
	v_exp_f32_e32 v5, v4
	v_mul_f32_e32 v4, 0xbfb8aa3b, v11
	v_exp_f32_e32 v14, v4
	v_pk_mul_f32 v[8:9], v[28:29], v[38:39]
	v_add_f32_e32 v5, 1.0, v5
	v_cvt_pk_bf16_f32 v4, v8, v9
	v_rcp_f32_e32 v8, v5
	v_add_f32_e32 v5, 1.0, v14
	v_pk_fma_f32 v[14:15], v[40:41], v[72:73], v[48:49]
	v_rcp_f32_e32 v9, v5
	v_pk_fma_f32 v[14:15], v[52:53], v[24:25], v[14:15]
	v_lshlrev_b32_e32 v20, 16, v6
	v_and_b32_e32 v21, 0xffff0000, v6
	v_pk_fma_f32 v[14:15], v[44:45], v[20:21], v[14:15]
	v_pk_mul_f32 v[8:9], v[10:11], v[8:9]
	v_mul_f32_e32 v5, 0xbfb8aa3b, v14
	v_exp_f32_e32 v5, v5
	v_mul_f32_e32 v6, 0xbfb8aa3b, v15
	v_exp_f32_e32 v27, v6
	v_pk_fma_f32 v[10:11], v[42:43], v[74:75], v[50:51]
	v_lshlrev_b32_e32 v28, 16, v7
	v_pk_fma_f32 v[10:11], v[54:55], v[16:17], v[10:11]
	v_and_b32_e32 v29, 0xffff0000, v7
	v_pk_fma_f32 v[10:11], v[46:47], v[28:29], v[10:11]
	v_add_f32_e32 v5, 1.0, v5
	v_mul_f32_e32 v7, 0xbfb8aa3b, v10
	v_rcp_f32_e32 v6, v5
	v_add_f32_e32 v5, 1.0, v27
	v_exp_f32_e32 v27, v7
	v_mul_f32_e32 v7, 0xbfb8aa3b, v11
	v_exp_f32_e32 v31, v7
	v_rcp_f32_e32 v7, v5
	v_add_f32_e32 v5, 1.0, v27
	v_rcp_f32_e32 v38, v5
	v_add_f32_e32 v5, 1.0, v31
	v_rcp_f32_e32 v39, v5
	v_cvt_pk_bf16_f32 v5, v8, v9
	v_pk_mul_f32 v[6:7], v[14:15], v[6:7]
	v_and_b32_e32 v15, 0xffff0000, v1
	v_pk_mul_f32 v[8:9], v[10:11], v[38:39]
	v_cvt_pk_bf16_f32 v6, v6, v7
	v_cvt_pk_bf16_f32 v7, v8, v9
	v_pk_fma_f32 v[8:9], v[56:57], v[18:19], v[60:61]
	v_lshlrev_b32_e32 v10, 16, v0
	v_pk_fma_f32 v[8:9], v[64:65], v[36:37], v[8:9]
	v_and_b32_e32 v11, 0xffff0000, v0
	v_pk_fma_f32 v[8:9], v[68:69], v[10:11], v[8:9]
	ds_write_b128 v30, v[4:7] offset:320
	v_mul_f32_e32 v0, 0xbfb8aa3b, v8
	v_exp_f32_e32 v0, v0
	v_mul_f32_e32 v14, 0xbfb8aa3b, v9
	v_exp_f32_e32 v14, v14
	v_pk_fma_f32 v[6:7], v[58:59], v[22:23], v[62:63]
	v_add_f32_e32 v0, 1.0, v0
	v_rcp_f32_e32 v4, v0
	v_add_f32_e32 v0, 1.0, v14
	v_pk_fma_f32 v[6:7], v[66:67], v[12:13], v[6:7]
	v_lshlrev_b32_e32 v14, 16, v1
	v_pk_fma_f32 v[6:7], v[70:71], v[14:15], v[6:7]
	v_rcp_f32_e32 v5, v0
	v_mul_f32_e32 v0, 0xbfb8aa3b, v6
	v_exp_f32_e32 v18, v0
	v_mul_f32_e32 v0, 0xbfb8aa3b, v7
	v_exp_f32_e32 v19, v0
	v_pk_mul_f32 v[0:1], v[8:9], v[4:5]
	v_pk_fma_f32 v[8:9], v[40:41], v[24:25], v[48:49]
	v_add_f32_e32 v4, 1.0, v18
	v_add_f32_e32 v5, 1.0, v19
	v_pk_fma_f32 v[8:9], v[52:53], v[20:21], v[8:9]
	v_lshlrev_b32_e32 v18, 16, v2
	v_and_b32_e32 v19, 0xffff0000, v2
; #define LAS __attribute__((address_space(3)))
; __device__ __forceinline__ unsigned cvtpk(float lo, float hi) { f32x2_t v = {lo, hi}; bf16x2_t b = __builtin_convertvector(v, bf16x2_t); return __builtin_bit_cast(unsigned, b); }
; template <class Put>
; __device__ __forceinline__ void conv_compute(const ConvRaw& R, const float* cw, const float* cb, int col0, int rg, const Put& put) {
;     const f32x4 w0a = *(const f32x4*)(cw + col0), w0b = *(const f32x4*)(cw + col0 + 4), w1a = *(const f32x4*)(cw + XBCW + col0), w1b = *(const f32x4*)(cw + XBCW + col0 + 4);
;     const f32x4 w2a = *(const f32x4*)(cw + 2 * XBCW + col0), w2b = *(const f32x4*)(cw + 2 * XBCW + col0 + 4), ba = *(const f32x4*)(cb + col0), bb = *(const f32x4*)(cb + col0 + 4);
;     const int r0 = 8 * rg;
; #pragma unroll
;     for (int rr = 0; rr < 8; ++rr) {
;         const u32x4 xm = R.r[rr], x0 = R.r[rr + 1], xp = R.r[rr + 2]; u32x4 o;
; #pragma unroll
;         for (int e = 0; e < 4; ++e) {
;             const float wl0 = e < 2 ? w0a[2 * e] : w0b[2 * e - 4], wh0 = e < 2 ? w0a[2 * e + 1] : w0b[2 * e - 3];
;             const float wl1 = e < 2 ? w1a[2 * e] : w1b[2 * e - 4], wh1 = e < 2 ? w1a[2 * e + 1] : w1b[2 * e - 3];
;             const float wl2 = e < 2 ? w2a[2 * e] : w2b[2 * e - 4], wh2 = e < 2 ? w2a[2 * e + 1] : w2b[2 * e - 3];
;             const float bl = e < 2 ? ba[2 * e] : bb[2 * e - 4], bh = e < 2 ? ba[2 * e + 1] : bb[2 * e - 3];
;             const float vl = bl + wl0 * lo16(xm[e]) + wl1 * lo16(x0[e]) + wl2 * lo16(xp[e]);
;             const float vh = bh + wh0 * hi16(xm[e]) + wh1 * hi16(x0[e]) + wh2 * hi16(xp[e]);
;             o[e] = cvtpk(silu_fast(vl), silu_fast(vh));
;         }
;         put(r0 + rr, o);
;     }
; }
; __device__ __forceinline__ void states_unit(Frame& F, const Ptrs& P, int b, int c, int g, int hh) {
;     ...
;     __syncthreads();
;     const int hl = wid >> 1, ph = wid & 1;
;     const int lbase = (int)(unsigned)(size_t)lds + ((lane >> 4) & 1) * 32 + (lane & 3) * 8 + (4 * hi + ((lane & 15) >> 2)) * 64;
;     const LAS float* Wf = (const LAS float*)(lds + L_VEC) + (hl * 2 + 0) * 512 + 384; const LAS float* Wb = (const LAS float*)(lds + L_VEC) + (hl * 2 + 1) * 512 + 384;
;     f32x16 af[4], ab[4];
; #pragma unroll
;     for (int i = 0; i < 4; ++i) { af[i] = f32x16{}; ab[i] = f32x16{}; }
	v_pk_fma_f32 v[8:9], v[44:45], v[18:19], v[8:9]
	v_rcp_f32_e32 v4, v4
	v_mul_f32_e32 v2, 0xbfb8aa3b, v8
	v_exp_f32_e32 v2, v2
	v_mul_f32_e32 v22, 0xbfb8aa3b, v9
	v_exp_f32_e32 v23, v22
	v_rcp_f32_e32 v5, v5
	v_add_f32_e32 v2, 1.0, v2
	v_rcp_f32_e32 v22, v2
	v_add_f32_e32 v2, 1.0, v23
	v_rcp_f32_e32 v23, v2
	v_pk_mul_f32 v[4:5], v[6:7], v[4:5]
	v_pk_fma_f32 v[6:7], v[42:43], v[16:17], v[50:51]
	v_cvt_pk_bf16_f32 v0, v0, v1
	v_cvt_pk_bf16_f32 v1, v4, v5
	v_pk_mul_f32 v[4:5], v[8:9], v[22:23]
	v_pk_fma_f32 v[6:7], v[54:55], v[28:29], v[6:7]
	v_lshlrev_b32_e32 v8, 16, v3
	v_and_b32_e32 v9, 0xffff0000, v3
	v_pk_fma_f32 v[6:7], v[46:47], v[8:9], v[6:7]
	v_pk_fma_f32 v[22:23], v[56:57], v[36:37], v[60:61]
	v_mul_f32_e32 v2, 0xbfb8aa3b, v6
	v_exp_f32_e32 v3, v2
	v_mul_f32_e32 v2, 0xbfb8aa3b, v7
	v_exp_f32_e32 v16, v2
	v_cvt_pk_bf16_f32 v2, v4, v5
	v_add_f32_e32 v3, 1.0, v3
	v_rcp_f32_e32 v4, v3
	v_add_f32_e32 v3, 1.0, v16
	v_lshlrev_b32_e32 v16, 16, v34
	v_and_b32_e32 v17, 0xffff0000, v34
	v_pk_fma_f32 v[10:11], v[64:65], v[10:11], v[22:23]
	s_nop 0
	v_pk_fma_f32 v[10:11], v[68:69], v[16:17], v[10:11]
	s_nop 0
	v_mul_f32_e32 v5, 0xbfb8aa3b, v10
	v_exp_f32_e32 v16, v5
	v_mul_f32_e32 v5, 0xbfb8aa3b, v11
	v_exp_f32_e32 v17, v5
	v_rcp_f32_e32 v5, v3
	v_add_f32_e32 v3, 1.0, v16
	v_rcp_f32_e32 v16, v3
	v_add_f32_e32 v3, 1.0, v17
	v_pk_mul_f32 v[4:5], v[6:7], v[4:5]
	v_rcp_f32_e32 v17, v3
	v_cvt_pk_bf16_f32 v3, v4, v5
	v_pk_fma_f32 v[4:5], v[58:59], v[12:13], v[62:63]
	ds_write_b128 v30, v[0:3] offset:384
	v_lshlrev_b32_e32 v2, 16, v33
	v_and_b32_e32 v3, 0xffff0000, v33
	v_pk_fma_f32 v[4:5], v[66:67], v[14:15], v[4:5]
	v_pk_mul_f32 v[0:1], v[10:11], v[16:17]
	v_pk_fma_f32 v[2:3], v[70:71], v[2:3], v[4:5]
	v_pk_fma_f32 v[10:11], v[40:41], v[20:21], v[48:49]
	v_mul_f32_e32 v4, 0xbfb8aa3b, v2
	v_exp_f32_e32 v4, v4
	v_mul_f32_e32 v5, 0xbfb8aa3b, v3
	v_exp_f32_e32 v5, v5
	v_cvt_pk_bf16_f32 v0, v0, v1
	v_add_f32_e32 v1, 1.0, v4
	v_lshlrev_b32_e32 v6, 16, v32
	v_and_b32_e32 v7, 0xffff0000, v32
	v_pk_fma_f32 v[10:11], v[52:53], v[18:19], v[10:11]
	v_rcp_f32_e32 v4, v1
	v_add_f32_e32 v1, 1.0, v5
	v_pk_fma_f32 v[6:7], v[44:45], v[6:7], v[10:11]
	v_rcp_f32_e32 v5, v1
	v_mul_f32_e32 v1, 0xbfb8aa3b, v6
	v_exp_f32_e32 v1, v1
	v_mul_f32_e32 v10, 0xbfb8aa3b, v7
	v_exp_f32_e32 v10, v10
	v_pk_mul_f32 v[2:3], v[2:3], v[4:5]
	v_add_f32_e32 v1, 1.0, v1
	v_rcp_f32_e32 v4, v1
	v_add_f32_e32 v1, 1.0, v10
	v_pk_fma_f32 v[10:11], v[42:43], v[28:29], v[50:51]
	v_mov_b32_e32 v48, 0
	v_pk_fma_f32 v[8:9], v[54:55], v[8:9], v[10:11]
	v_lshlrev_b32_e32 v10, 16, v26
	v_and_b32_e32 v11, 0xffff0000, v26
	v_pk_fma_f32 v[8:9], v[46:47], v[10:11], v[8:9]
	v_mov_b32_e32 v49, v48
	v_mul_f32_e32 v5, 0xbfb8aa3b, v8
	v_exp_f32_e32 v10, v5
	v_mul_f32_e32 v5, 0xbfb8aa3b, v9
	v_exp_f32_e32 v11, v5
	v_rcp_f32_e32 v5, v1
	v_add_f32_e32 v1, 1.0, v10
	v_rcp_f32_e32 v10, v1
	v_add_f32_e32 v1, 1.0, v11
	v_rcp_f32_e32 v11, v1
	v_cvt_pk_bf16_f32 v1, v2, v3
	v_pk_mul_f32 v[2:3], v[6:7], v[4:5]
	v_mov_b32_e32 v50, v48
	v_pk_mul_f32 v[4:5], v[8:9], v[10:11]
	v_cvt_pk_bf16_f32 v2, v2, v3
	v_cvt_pk_bf16_f32 v3, v4, v5
	ds_write_b128 v30, v[0:3] offset:448
	v_lshlrev_b32_e32 v0, 1, v100
	v_lshlrev_b32_e32 v1, 3, v100
	v_lshlrev_b32_e32 v2, 8, v128
	v_and_b32_e32 v3, 0xc0, v141
	v_and_b32_e32 v0, 32, v0
	v_and_b32_e32 v1, 24, v1
	v_add3_u32 v4, v2, 0, v3
	v_add3_u32 v2, s76, v2, v3
	v_add3_u32 v143, v4, v0, v1
	v_add3_u32 v144, v2, v0, v1
	v_mov_b32_e32 v51, v48
	v_mov_b32_e32 v52, v48
	v_mov_b32_e32 v53, v48
	v_mov_b32_e32 v54, v48
	v_mov_b32_e32 v55, v48
	v_mov_b32_e32 v56, v48
	v_mov_b32_e32 v57, v48
	v_mov_b32_e32 v58, v48
	v_mov_b32_e32 v59, v48
	v_mov_b32_e32 v60, v48
	v_mov_b32_e32 v61, v48
	v_mov_b32_e32 v62, v48
	v_mov_b32_e32 v63, v48
	v_mov_b32_e32 v32, v48
	v_mov_b32_e32 v33, v48
	v_mov_b32_e32 v34, v48
	v_mov_b32_e32 v35, v48
	v_mov_b32_e32 v36, v48
	v_mov_b32_e32 v37, v48
	v_mov_b32_e32 v38, v48
	v_mov_b32_e32 v39, v48
	v_mov_b32_e32 v40, v48
	v_mov_b32_e32 v41, v48
	v_mov_b32_e32 v42, v48
	v_mov_b32_e32 v43, v48
	v_mov_b32_e32 v44, v48
	v_mov_b32_e32 v45, v48
	v_mov_b32_e32 v46, v48
	v_mov_b32_e32 v47, v48
	v_mov_b32_e32 v16, v48
	v_mov_b32_e32 v17, v48
	v_mov_b32_e32 v18, v48
	v_mov_b32_e32 v19, v48
	v_mov_b32_e32 v20, v48
	v_mov_b32_e32 v21, v48
	v_mov_b32_e32 v22, v48
	v_mov_b32_e32 v23, v48
	v_mov_b32_e32 v24, v48
	v_mov_b32_e32 v25, v48
	v_mov_b32_e32 v26, v48
	v_mov_b32_e32 v27, v48
	v_mov_b32_e32 v28, v48
	v_mov_b32_e32 v29, v48
	v_mov_b32_e32 v30, v48
	v_mov_b32_e32 v31, v48
	v_mov_b32_e32 v0, v48
	v_mov_b32_e32 v1, v48
	v_mov_b32_e32 v2, v48
	v_mov_b32_e32 v3, v48
	v_mov_b32_e32 v4, v48
	v_mov_b32_e32 v5, v48
	v_mov_b32_e32 v6, v48
	v_mov_b32_e32 v7, v48
	v_mov_b32_e32 v8, v48
	v_mov_b32_e32 v9, v48
	v_mov_b32_e32 v10, v48
	v_mov_b32_e32 v11, v48
	v_mov_b32_e32 v12, v48
	v_mov_b32_e32 v13, v48
	v_mov_b32_e32 v14, v48
	v_mov_b32_e32 v15, v48
	v_mov_b32_e32 v112, v48
	v_mov_b32_e32 v113, v48
	v_mov_b32_e32 v114, v48
	v_mov_b32_e32 v115, v48
	v_mov_b32_e32 v116, v48
	v_mov_b32_e32 v117, v48
	v_mov_b32_e32 v118, v48
	v_mov_b32_e32 v119, v48
	v_mov_b32_e32 v120, v48
	v_mov_b32_e32 v121, v48
	v_mov_b32_e32 v122, v48
	v_mov_b32_e32 v123, v48
	v_mov_b32_e32 v124, v48
	v_mov_b32_e32 v125, v48
	v_mov_b32_e32 v126, v48
	v_mov_b32_e32 v127, v48
	v_mov_b32_e32 v96, v48
	v_mov_b32_e32 v97, v48
	v_mov_b32_e32 v98, v48
	v_mov_b32_e32 v99, v48
	v_mov_b32_e32 v100, v48
	v_mov_b32_e32 v101, v48
	v_mov_b32_e32 v102, v48
	v_mov_b32_e32 v103, v48
	v_mov_b32_e32 v104, v48
	v_mov_b32_e32 v105, v48
	v_mov_b32_e32 v106, v48
	v_mov_b32_e32 v107, v48
	v_mov_b32_e32 v108, v48
	v_mov_b32_e32 v109, v48
	v_mov_b32_e32 v110, v48
	v_mov_b32_e32 v111, v48
	v_mov_b32_e32 v80, v48
	v_mov_b32_e32 v81, v48
	v_mov_b32_e32 v82, v48
	v_mov_b32_e32 v83, v48
	v_mov_b32_e32 v84, v48
	v_mov_b32_e32 v85, v48
	v_mov_b32_e32 v86, v48
	v_mov_b32_e32 v87, v48
	v_mov_b32_e32 v88, v48
	v_mov_b32_e32 v89, v48
	v_mov_b32_e32 v90, v48
	v_mov_b32_e32 v91, v48
	v_mov_b32_e32 v92, v48
	v_mov_b32_e32 v93, v48
	v_mov_b32_e32 v94, v48
	v_mov_b32_e32 v95, v48
	v_mov_b32_e32 v64, v48
	v_mov_b32_e32 v65, v48
	v_mov_b32_e32 v66, v48
	v_mov_b32_e32 v67, v48
	v_mov_b32_e32 v68, v48
	v_mov_b32_e32 v69, v48
	v_mov_b32_e32 v70, v48
	v_mov_b32_e32 v71, v48
	v_mov_b32_e32 v72, v48
	v_mov_b32_e32 v73, v48
	v_mov_b32_e32 v74, v48
	v_mov_b32_e32 v75, v48
	v_mov_b32_e32 v76, v48
	v_mov_b32_e32 v77, v48
	v_mov_b32_e32 v78, v48
	v_mov_b32_e32 v79, v48
	s_waitcnt lgkmcnt(0)
	s_barrier

; __device__ __forceinline__ void conv_load(ConvRaw& R, const bf16* XBC, int b, int c, int col0, int rg) {
;     const int r0 = 8 * rg;
; #pragma unroll
;     for (int i = 0; i < 10; ++i) { int t = c * 128 + r0 - 1 + i; t = t < 0 ? 0 : (t > SEQ - 1 ? SEQ - 1 : t); R.r[i] = *(const u32x4*)(XBC + ((size_t)b * SEQ + t) * XBCW + col0); }
;     if (c == 0 && rg == 0) R.r[0] = (u32x4){0u, 0u, 0u, 0u};
;     if (c == 63 && rg == 15) R.r[9] = (u32x4){0u, 0u, 0u, 0u};
; }
; template <class Put>
; __device__ __forceinline__ void conv_compute(const ConvRaw& R, const float* cw, const float* cb, int col0, int rg, const Put& put) {
;     const f32x4 w0a = *(const f32x4*)(cw + col0), w0b = *(const f32x4*)(cw + col0 + 4), w1a = *(const f32x4*)(cw + XBCW + col0), w1b = *(const f32x4*)(cw + XBCW + col0 + 4);
;     const f32x4 w2a = *(const f32x4*)(cw + 2 * XBCW + col0), w2b = *(const f32x4*)(cw + 2 * XBCW + col0 + 4), ba = *(const f32x4*)(cb + col0), bb = *(const f32x4*)(cb + col0 + 4);
;     const int r0 = 8 * rg;
; #pragma unroll
;     for (int rr = 0; rr < 8; ++rr) {
;         const u32x4 xm = R.r[rr], x0 = R.r[rr + 1], xp = R.r[rr + 2]; u32x4 o;
; #pragma unroll
;         for (int e = 0; e < 4; ++e) {
;             const float wl0 = e < 2 ? w0a[2 * e] : w0b[2 * e - 4], wh0 = e < 2 ? w0a[2 * e + 1] : w0b[2 * e - 3];
;             const float wl1 = e < 2 ? w1a[2 * e] : w1b[2 * e - 4], wh1 = e < 2 ? w1a[2 * e + 1] : w1b[2 * e - 3];
;             const float wl2 = e < 2 ? w2a[2 * e] : w2b[2 * e - 4], wh2 = e < 2 ? w2a[2 * e + 1] : w2b[2 * e - 3];
; __device__ __forceinline__ void states_unit(Frame& F, const Ptrs& P, int b, int c, int g, int hh) {
;     ...
;     {
;         ConvRawN<4> Rb; ConvRaw Rx; const int chb = tid & 15, rgb = tid >> 4, hlx = tid >> 7, chx = tid & 7, rgx = (tid >> 3) & 15;
;         conv_load_n<4>(Rb, XBC, b, c, 1024 + g * 128 + 8 * chb, rgb);
;         conv_load(Rx, XBC, b, c, (h0 + hlx) * 64 + 8 * chx, rgx);
;         if (wid == 0 && lane == 0) { const unsigned* fl = (const unsigned*)(P.ws + WS_CTL) + CW_DTF + (b * 128 + 2 * c); unsigned sp = 0u;
;             while ((__hip_atomic_load(fl, __ATOMIC_RELAXED, __HIP_MEMORY_SCOPE_AGENT) & __hip_atomic_load(fl + 1, __ATOMIC_RELAXED, __HIP_MEMORY_SCOPE_AGENT)) == 0u) { __builtin_amdgcn_s_sleep(1); if (++sp > (1u << 22)) break; } }
.Lst2_562:
	s_bfe_u32 s84, s83, 0x60002
	s_bfe_u32 s0, s83, 0x10001
	v_mbcnt_lo_u32_b32 v0, -1, 0
	v_mbcnt_hi_u32_b32 v0, -1, v0
	s_lshl_b32 s2, s83, 2
	v_add_u32_e32 v100, s60, v0
	s_lshl_b32 s1, s0, 3
	s_and_b32 s2, s2, 4
	v_ashrrev_i32_e32 v99, 4, v100
	s_lshl_b32 s85, s84, 7
	s_ashr_i32 s70, s83, 8
	s_or_b32 s16, s1, s2
	v_and_b32_e32 v98, 15, v100
	s_lshl_b32 s0, s0, 7
	v_lshlrev_b32_e32 v2, 2, v99
	s_add_i32 s2, s85, -1
	v_lshl_or_b32 v0, v98, 3, s0
	v_add_u32_e32 v4, s2, v2
	s_ashr_i32 s71, s70, 31
	v_or_b32_e32 v56, 0x400, v0
	s_lshl_b64 s[4:5], s[70:71], 13
	v_med3_i32 v0, v4, 0, v132
	v_add_u32_e32 v2, s85, v2
	v_or_b32_e32 v0, s4, v0
	v_med3_i32 v2, v2, 0, v132
	s_waitcnt lgkmcnt(0)
	v_mad_u64_u32 v[0:1], s[0:1], v0, s77, v[130:131]
	v_or_b32_e32 v2, s4, v2
	v_mad_i32_i24 v1, s5, v133, v1
	v_lshlrev_b32_e32 v128, 1, v56
	v_mad_u64_u32 v[2:3], s[0:1], v2, s77, v[130:131]
	v_lshl_add_u64 v[0:1], v[0:1], 0, v[128:129]
	v_mad_i32_i24 v3, s5, v133, v3
	v_lshl_add_u64 v[2:3], v[2:3], 0, v[128:129]
	s_waitcnt vmcnt(32)
	v_mov_b32_e32 v88, v188
	v_mov_b32_e32 v89, v189
	v_mov_b32_e32 v90, v190
	v_mov_b32_e32 v91, v191
	v_mov_b32_e32 v48, v192
	v_mov_b32_e32 v49, v193
	v_mov_b32_e32 v50, v194
	v_mov_b32_e32 v51, v195
	v_max_i32_e32 v0, -2, v4
	v_add_u32_e32 v0, 2, v0
	v_max_i32_e32 v2, -3, v4
	v_min_u32_e32 v0, 0x1fff, v0
	v_add_u32_e32 v2, 3, v2
	v_or_b32_e32 v0, s4, v0
	v_min_u32_e32 v2, 0x1fff, v2
	v_mad_u64_u32 v[0:1], s[0:1], v0, s77, v[130:131]
	v_or_b32_e32 v2, s4, v2
	v_mad_i32_i24 v1, s5, v133, v1
	v_mad_u64_u32 v[2:3], s[0:1], v2, s77, v[130:131]
	v_lshl_add_u64 v[0:1], v[0:1], 0, v[128:129]
	v_mad_i32_i24 v3, s5, v133, v3
	v_lshl_add_u64 v[2:3], v[2:3], 0, v[128:129]
	v_mov_b32_e32 v52, v196
	v_mov_b32_e32 v53, v197
	v_mov_b32_e32 v54, v198
	v_mov_b32_e32 v55, v199
	v_mov_b32_e32 v44, v200
	v_mov_b32_e32 v45, v201
	v_mov_b32_e32 v46, v202
	v_mov_b32_e32 v47, v203
	v_max_i32_e32 v0, -4, v4
	v_add_u32_e32 v0, 4, v0
	v_max_i32_e32 v2, -5, v4
	v_min_u32_e32 v0, 0x1fff, v0
	v_add_u32_e32 v2, 5, v2
	v_or_b32_e32 v0, s4, v0
	v_min_u32_e32 v2, 0x1fff, v2
	v_mad_u64_u32 v[0:1], s[0:1], v0, s77, v[130:131]
	v_or_b32_e32 v2, s4, v2
	v_mad_i32_i24 v1, s5, v133, v1
	v_mad_u64_u32 v[2:3], s[0:1], v2, s77, v[130:131]
	v_ashrrev_i32_e32 v103, 7, v100
	v_and_b32_e32 v101, 7, v100
	v_bfe_u32 v102, v100, 3, 4
	v_lshl_add_u64 v[0:1], v[0:1], 0, v[128:129]
	v_mad_i32_i24 v3, s5, v133, v3
	v_lshl_add_u64 v[2:3], v[2:3], 0, v[128:129]
	v_mov_b32_e32 v40, v204
	v_mov_b32_e32 v41, v205
	v_mov_b32_e32 v42, v206
	v_mov_b32_e32 v43, v207
	v_mov_b32_e32 v92, v208
	v_mov_b32_e32 v93, v209
	v_mov_b32_e32 v94, v210
	v_mov_b32_e32 v95, v211
	v_add_u32_e32 v0, s16, v103
	v_lshlrev_b32_e32 v1, 3, v101
	v_lshlrev_b32_e32 v6, 3, v102
	v_lshl_or_b32 v96, v0, 6, v1
	v_add_u32_e32 v38, s2, v6
	v_ashrrev_i32_e32 v97, 31, v96
	v_max_i32_e32 v128, 0, v38
	v_lshl_add_u64 v[0:1], v[96:97], 1, s[10:11]
	v_lshl_add_u64 v[2:3], s[4:5], 0, v[128:129]
	v_mad_u64_u32 v[4:5], s[0:1], v2, s77, v[0:1]
	v_or_b32_e32 v2, s85, v6
	v_or_b32_e32 v2, s4, v2
	v_mad_i32_i24 v5, v3, s77, v5
	v_mad_u64_u32 v[2:3], s[0:1], v2, s77, v[0:1]
	v_mad_i32_i24 v3, s5, v133, v3
	v_add_u32_e32 v128, 2, v38
	v_mov_b32_e32 v32, v212
	v_mov_b32_e32 v33, v213
	v_mov_b32_e32 v34, v214
	v_mov_b32_e32 v35, v215
	v_mov_b32_e32 v24, v216
	v_mov_b32_e32 v25, v217
	v_mov_b32_e32 v26, v218
	v_mov_b32_e32 v27, v219
	v_lshl_add_u64 v[2:3], s[4:5], 0, v[128:129]
	v_mad_u64_u32 v[4:5], s[0:1], v2, s77, v[0:1]
	v_add_u32_e32 v128, 3, v38
	v_mad_i32_i24 v5, v3, s77, v5
	v_lshl_add_u64 v[2:3], s[4:5], 0, v[128:129]
	v_mad_u64_u32 v[6:7], s[0:1], v2, s77, v[0:1]
	v_add_u32_e32 v128, 4, v38
	v_mad_i32_i24 v7, v3, s77, v7
	v_lshl_add_u64 v[2:3], s[4:5], 0, v[128:129]
	v_mov_b32_e32 v28, v220
	v_mov_b32_e32 v29, v221
	v_mov_b32_e32 v30, v222
	v_mov_b32_e32 v31, v223
	v_mov_b32_e32 v20, v224
	v_mov_b32_e32 v21, v225
	v_mov_b32_e32 v22, v226
	v_mov_b32_e32 v23, v227
	v_mad_u64_u32 v[4:5], s[0:1], v2, s77, v[0:1]
	v_add_u32_e32 v128, 5, v38
	v_mad_i32_i24 v5, v3, s77, v5
	v_lshl_add_u64 v[2:3], s[4:5], 0, v[128:129]
	v_mad_u64_u32 v[6:7], s[0:1], v2, s77, v[0:1]
	v_add_u32_e32 v128, 6, v38
	v_mad_i32_i24 v7, v3, s77, v7
	v_lshl_add_u64 v[2:3], s[4:5], 0, v[128:129]
	v_mov_b32_e32 v16, v228
	v_mov_b32_e32 v17, v229
	v_mov_b32_e32 v18, v230
	v_mov_b32_e32 v19, v231
	v_mov_b32_e32 v12, v232
	v_mov_b32_e32 v13, v233
	v_mov_b32_e32 v14, v234
	v_mov_b32_e32 v15, v235
	v_mad_u64_u32 v[4:5], s[0:1], v2, s77, v[0:1]
	v_add_u32_e32 v128, 7, v38
	v_mad_i32_i24 v5, v3, s77, v5
	v_lshl_add_u64 v[2:3], s[4:5], 0, v[128:129]
	v_mad_u64_u32 v[6:7], s[0:1], v2, s77, v[0:1]
	v_add_u32_e32 v128, 8, v38
	v_mad_i32_i24 v7, v3, s77, v7
	v_lshl_add_u64 v[2:3], s[4:5], 0, v[128:129]
	v_mad_u64_u32 v[36:37], s[0:1], v2, s77, v[0:1]
	v_add_u32_e32 v2, 9, v38
	v_min_u32_e32 v2, 0x1fff, v2
	v_or_b32_e32 v2, s4, v2
	v_mad_u64_u32 v[38:39], s[0:1], v2, s77, v[0:1]
	v_mad_i32_i24 v37, v3, s77, v37
	v_mad_i32_i24 v39, s5, v133, v39
	v_mov_b32_e32 v8, v236
	v_mov_b32_e32 v9, v237
	v_mov_b32_e32 v10, v238
	v_mov_b32_e32 v11, v239
	s_nop 0
	v_mov_b32_e32 v4, v240
	v_mov_b32_e32 v5, v241
	v_mov_b32_e32 v6, v242
	v_mov_b32_e32 v7, v243
	s_nop 0
	v_mov_b32_e32 v0, v244
	v_mov_b32_e32 v1, v245
	v_mov_b32_e32 v2, v246
	v_mov_b32_e32 v3, v247
	s_nop 0
	v_mov_b32_e32 v36, v248
	v_mov_b32_e32 v37, v249
	v_mov_b32_e32 v38, v250
	v_mov_b32_e32 v39, v251
	v_and_b32_e32 v104, 63, v100
	v_readlane_b32 s0, v252, 5
	s_nop 1
	v_or_b32_e32 v57, s0, v104
	v_cmp_eq_u32_e32 vcc, 0, v57
	s_and_saveexec_b64 s[0:1], vcc
	s_cbranch_execz .Lst2_571
	s_lshl_b32 s2, s70, 7
	s_lshl_b32 s3, s84, 1
	s_or_b32 s2, s3, s2
	s_ashr_i32 s3, s2, 31
	s_lshl_b64 s[2:3], s[2:3], 2
	s_add_u32 s2, s33, s2
	s_addc_u32 s3, s34, s3
	s_mov_b32 s72, 0x400001
	s_branch .Lst2_565

; #define LAS __attribute__((address_space(3)))
; #define SSD_SBAR() __builtin_amdgcn_sched_barrier(0)
; __device__ __forceinline__ void states_unit(Frame& F, const Ptrs& P, int b, int c, int g, int hh) {
;     ...
; #pragma unroll 2
;     for (int ks = 0; ks < 8; ++ks) {
;         s16x4 xl, xh, bl[4], bh[4];
;         f32x4 wfa = *(const LAS f32x4*)(Wf + 16 * ks + 4 * hi), wfb = *(const LAS f32x4*)(Wf + 16 * ks + 8 + 4 * hi);
;         f32x4 wba = *(const LAS f32x4*)(Wb + 16 * ks + 4 * hi), wbb = *(const LAS f32x4*)(Wb + 16 * ks + 8 + 4 * hi);
;         asm volatile("" : "+v"(wfa), "+v"(wfb), "+v"(wba), "+v"(wbb));
;         SSD_SBAR();
;         tr2(xl, xh, lbase + L_XS + hl * 16384 + (ph * 8 + ks) * 1024);
; #pragma unroll
;         for (int nb = 0; nb < 4; ++nb) tr2(bl[nb], bh[nb], lbase + L_BIMG + (nb * 8 + ks) * 1024);
;         asm volatile("s_waitcnt lgkmcnt(0)" ::: "memory"); SSD_SBAR();
;         const bf16x8 xf = scale_frag(xl, xh, wfa, wfb), xb = scale_frag(xl, xh, wba, wbb);
; #pragma unroll
;         for (int nb = 0; nb < 4; ++nb) { const bf16x8 bfr = SSD_FRAG(bl[nb], bh[nb]);
;             af[nb] = __builtin_amdgcn_mfma_f32_32x32x16_bf16(bfr, xf, af[nb], 0, 0, 0); ab[nb] = __builtin_amdgcn_mfma_f32_32x32x16_bf16(bfr, xb, ab[nb], 0, 0, 0); }
;     }
.Lst2_578:
	v_add_u32_e32 v145, s64, v142
	v_add_u32_e32 v184, s75, v142
	v_add_u32_e32 v158, 0x20600, v145
	v_add_u32_e32 v154, 0x20620, v145
	v_add_u32_e32 v150, 0x20600, v184
	v_add_u32_e32 v146, 0x20620, v184
	ds_read_b128 v[146:149], v146
	ds_read_b128 v[150:153], v150
	ds_read_b128 v[154:157], v154
	ds_read_b128 v[158:161], v158
	s_waitcnt lgkmcnt(0)
	v_add_u32_e32 v185, s2, v144
	v_add_u32_e32 v162, 0x10000, v185
	ds_read_b64_tr_b16 v[178:179],v162
	ds_read_b64_tr_b16 v[180:181],v162 offset:512
	v_add_u32_e32 v186, s2, v143
	ds_read_b64_tr_b16 v[162:163],v186
	ds_read_b64_tr_b16 v[164:165],v186 offset:512
	v_add_u32_e32 v170, 0x2000, v186
	ds_read_b64_tr_b16 v[166:167],v170
	ds_read_b64_tr_b16 v[168:169],v170 offset:512
	v_add_u32_e32 v174, 0x4000, v186
	ds_read_b64_tr_b16 v[170:171],v174
	ds_read_b64_tr_b16 v[172:173],v174 offset:512
	v_add_u32_e32 v182, 0x6000, v186
	ds_read_b64_tr_b16 v[174:175],v182
	ds_read_b64_tr_b16 v[176:177],v182 offset:512
	s_waitcnt lgkmcnt(0)
	v_and_b32_e32 v183, 0xffff0000, v178
	v_lshlrev_b32_e32 v182, 16, v178
	v_pk_mul_f32 v[158:159], v[158:159], v[182:183]
	v_pk_mul_f32 v[150:151], v[150:151], v[182:183]
	v_and_b32_e32 v183, 0xffff0000, v179
	v_lshlrev_b32_e32 v182, 16, v179
	v_and_b32_e32 v179, 0xffff0000, v180
	v_lshlrev_b32_e32 v178, 16, v180
	v_pk_mul_f32 v[160:161], v[160:161], v[182:183]
	v_pk_mul_f32 v[154:155], v[154:155], v[178:179]
	v_cvt_pk_bf16_f32 v158, v158, v159
	v_cvt_pk_bf16_f32 v159, v160, v161
	v_cvt_pk_bf16_f32 v160, v154, v155
	v_and_b32_e32 v155, 0xffff0000, v181
	v_lshlrev_b32_e32 v154, 16, v181
	v_pk_mul_f32 v[152:153], v[152:153], v[182:183]
	v_pk_mul_f32 v[146:147], v[146:147], v[178:179]
	v_pk_mul_f32 v[156:157], v[156:157], v[154:155]
	v_cvt_pk_bf16_f32 v150, v150, v151
	v_cvt_pk_bf16_f32 v151, v152, v153
	v_cvt_pk_bf16_f32 v152, v146, v147
	v_pk_mul_f32 v[146:147], v[148:149], v[154:155]
	v_cvt_pk_bf16_f32 v161, v156, v157
	v_cvt_pk_bf16_f32 v153, v146, v147
	v_add_u32_e32 v154, 0x20640, v184
	v_mfma_f32_32x32x16_bf16 v[112:127], v[162:165], v[158:161], v[112:127]
	v_add_u32_e32 v146, 0x20660, v184
	v_mfma_f32_32x32x16_bf16 v[48:63], v[162:165], v[150:153], v[48:63]
	v_add_u32_e32 v162, 0x20640, v145
	v_add_u32_e32 v145, 0x20660, v145
	v_mfma_f32_32x32x16_bf16 v[96:111], v[166:169], v[158:161], v[96:111]
	v_mfma_f32_32x32x16_bf16 v[32:47], v[166:169], v[150:153], v[32:47]
	v_mfma_f32_32x32x16_bf16 v[80:95], v[170:173], v[158:161], v[80:95]
	v_mfma_f32_32x32x16_bf16 v[16:31], v[170:173], v[150:153], v[16:31]
	v_mfma_f32_32x32x16_bf16 v[64:79], v[174:177], v[158:161], v[64:79]
	ds_read_b128 v[146:149], v146
	ds_read_b128 v[154:157], v154
	ds_read_b128 v[158:161], v145
	ds_read_b128 v[162:165], v162
	s_waitcnt lgkmcnt(0)
	v_mfma_f32_32x32x16_bf16 v[0:15], v[174:177], v[150:153], v[0:15]
	v_add_u32_e32 v145, 0x10400, v185
	ds_read_b64_tr_b16 v[178:179],v145
	ds_read_b64_tr_b16 v[180:181],v145 offset:512
	v_add_u32_e32 v145, 0x400, v186
	ds_read_b64_tr_b16 v[150:151],v145
	ds_read_b64_tr_b16 v[152:153],v145 offset:512
	v_add_u32_e32 v145, 0x2400, v186
	ds_read_b64_tr_b16 v[166:167],v145
	ds_read_b64_tr_b16 v[168:169],v145 offset:512
	v_add_u32_e32 v145, 0x4400, v186
	ds_read_b64_tr_b16 v[170:171],v145
	ds_read_b64_tr_b16 v[172:173],v145 offset:512
	v_add_u32_e32 v145, 0x6400, v186
	ds_read_b64_tr_b16 v[174:175],v145
	ds_read_b64_tr_b16 v[176:177],v145 offset:512
	s_waitcnt lgkmcnt(0)
	v_and_b32_e32 v183, 0xffff0000, v178
	v_lshlrev_b32_e32 v182, 16, v178
	v_pk_mul_f32 v[162:163], v[162:163], v[182:183]
	v_pk_mul_f32 v[154:155], v[154:155], v[182:183]
	v_and_b32_e32 v183, 0xffff0000, v179
	v_lshlrev_b32_e32 v182, 16, v179
	v_and_b32_e32 v179, 0xffff0000, v180
	v_lshlrev_b32_e32 v178, 16, v180
	v_pk_mul_f32 v[164:165], v[164:165], v[182:183]
	v_pk_mul_f32 v[158:159], v[158:159], v[178:179]
	v_cvt_pk_bf16_f32 v162, v162, v163
	v_cvt_pk_bf16_f32 v163, v164, v165
	v_cvt_pk_bf16_f32 v164, v158, v159
	v_and_b32_e32 v159, 0xffff0000, v181
	v_lshlrev_b32_e32 v158, 16, v181
	v_pk_mul_f32 v[156:157], v[156:157], v[182:183]
	v_pk_mul_f32 v[146:147], v[146:147], v[178:179]
	v_pk_mul_f32 v[160:161], v[160:161], v[158:159]
	v_cvt_pk_bf16_f32 v154, v154, v155
	v_cvt_pk_bf16_f32 v155, v156, v157
	v_cvt_pk_bf16_f32 v156, v146, v147
	v_pk_mul_f32 v[146:147], v[148:149], v[158:159]
	v_cvt_pk_bf16_f32 v165, v160, v161
	v_cvt_pk_bf16_f32 v157, v146, v147
	s_addk_i32 s2, 0x800
	v_mfma_f32_32x32x16_bf16 v[112:127], v[150:153], v[162:165], v[112:127]
	v_add_u32_e32 v142, 0x80, v142
	s_cmpk_lg_i32 s2, 0x2000
	v_mfma_f32_32x32x16_bf16 v[48:63], v[150:153], v[154:157], v[48:63]
	v_mfma_f32_32x32x16_bf16 v[96:111], v[166:169], v[162:165], v[96:111]
	v_mfma_f32_32x32x16_bf16 v[32:47], v[166:169], v[154:157], v[32:47]
	v_mfma_f32_32x32x16_bf16 v[80:95], v[170:173], v[162:165], v[80:95]
	v_mfma_f32_32x32x16_bf16 v[16:31], v[170:173], v[154:157], v[16:31]
	v_mfma_f32_32x32x16_bf16 v[64:79], v[174:177], v[162:165], v[64:79]
	v_mfma_f32_32x32x16_bf16 v[0:15], v[174:177], v[154:157], v[0:15]
	s_cbranch_scc1 .Lst2_578
; __device__ __forceinline__ unsigned cvtpk(float lo, float hi) { f32x2_t v = {lo, hi}; bf16x2_t b = __builtin_convertvector(v, bf16x2_t); return __builtin_bit_cast(unsigned, b); }
; __device__ __forceinline__ unsigned cvtpk(float lo, float hi) { f32x2_t v = {lo, hi}; bf16x2_t b = __builtin_convertvector(v, bf16x2_t); return __builtin_bit_cast(unsigned, b); }
; __device__ __forceinline__ void states_unit(Frame& F, const Ptrs& P, int b, int c, int g, int hh) {
;     ...
;     const int h = h0 + hl;
; #pragma unroll
;     for (int dir = 0; dir < 2; ++dir) {
;         unsigned char* blk = SB + ((((size_t)b * 64 + c) * 2 + dir) * 16 + h) * 16384;
; #pragma unroll
;         for (int nb = 0; nb < 4; ++nb)
; #pragma unroll
;             for (int g4 = 0; g4 < 4; ++g4) { const f32x16& a = dir ? ab[nb] : af[nb];
;                 u32x2 w; w.x = cvtpk(a[4 * g4], a[4 * g4 + 1]); w.y = cvtpk(a[4 * g4 + 2], a[4 * g4 + 3]);
;                 *(u32x2*)(blk + ((((ph * 8 + 2 * nb + (g4 >> 1)) * 2 + (g4 & 1)) * 32 + r32) * 16) + hi * 8) = w; }
;     }
;     __syncthreads();
	s_lshl_b32 s0, s84, 19
	s_lshl_b64 s[2:3], s[16:17], 14
	s_add_u32 s2, s58, s2
	s_addc_u32 s3, s59, s3
	v_lshlrev_b32_e32 v128, 3, v128
	v_lshl_add_u64 v[142:143], s[2:3], 0, v[128:129]
	s_lshl_b64 s[2:3], s[70:71], 25
	v_and_b32_e32 v141, 0x1f0, v141
	s_mov_b32 s1, s17
	v_lshl_add_u64 v[142:143], v[142:143], 0, s[2:3]
	v_lshl_add_u64 v[142:143], v[142:143], 0, s[0:1]
	v_or_b32_e32 v128, s74, v141
	v_cvt_pk_bf16_f32 v112, v112, v113
	v_cvt_pk_bf16_f32 v113, v114, v115
	v_lshl_add_u64 v[114:115], v[142:143], 0, v[128:129]
	v_cvt_pk_bf16_f32 v96, v96, v97
	v_cvt_pk_bf16_f32 v97, v98, v99
	global_store_dwordx2 v[114:115], v[96:97], off offset:2048
	v_cvt_pk_bf16_f32 v96, v100, v101
	v_cvt_pk_bf16_f32 v97, v102, v103
	global_store_dwordx2 v[114:115], v[96:97], off offset:2560
	v_cvt_pk_bf16_f32 v96, v104, v105
	v_cvt_pk_bf16_f32 v97, v106, v107
	global_store_dwordx2 v[114:115], v[96:97], off offset:3072
	v_cvt_pk_bf16_f32 v96, v108, v109
	v_cvt_pk_bf16_f32 v97, v110, v111
	v_cvt_pk_bf16_f32 v80, v80, v81
	v_cvt_pk_bf16_f32 v81, v82, v83
	v_or_b32_e32 v82, 0x1000, v128
	v_mov_b32_e32 v83, v129
	global_store_dwordx2 v[114:115], v[96:97], off offset:3584
	v_lshl_add_u64 v[96:97], v[142:143], 0, v[82:83]
	global_store_dwordx2 v[96:97], v[80:81], off
	v_cvt_pk_bf16_f32 v80, v84, v85
	v_or_b32_e32 v84, 0x1200, v128
	v_mov_b32_e32 v85, v129
	v_cvt_pk_bf16_f32 v81, v86, v87
	v_lshl_add_u64 v[86:87], v[142:143], 0, v[84:85]
	global_store_dwordx2 v[86:87], v[80:81], off
	v_or_b32_e32 v86, 0x1400, v128
	v_mov_b32_e32 v87, v129
	v_cvt_pk_bf16_f32 v80, v88, v89
	v_cvt_pk_bf16_f32 v81, v90, v91
	v_lshl_add_u64 v[88:89], v[142:143], 0, v[86:87]
	global_store_dwordx2 v[88:89], v[80:81], off
	v_or_b32_e32 v88, 0x1600, v128
	v_mov_b32_e32 v89, v129
	v_cvt_pk_bf16_f32 v80, v92, v93
	v_cvt_pk_bf16_f32 v81, v94, v95
	v_lshl_add_u64 v[90:91], v[142:143], 0, v[88:89]
	v_cvt_pk_bf16_f32 v64, v64, v65
	v_cvt_pk_bf16_f32 v65, v66, v67
	v_or_b32_e32 v66, 0x1800, v128
	v_mov_b32_e32 v67, v129
	global_store_dwordx2 v[90:91], v[80:81], off
	v_lshl_add_u64 v[80:81], v[142:143], 0, v[66:67]
	global_store_dwordx2 v[80:81], v[64:65], off
	v_cvt_pk_bf16_f32 v64, v68, v69
	v_or_b32_e32 v68, 0x1a00, v128
	v_mov_b32_e32 v69, v129
	v_cvt_pk_bf16_f32 v65, v70, v71
	v_lshl_add_u64 v[70:71], v[142:143], 0, v[68:69]
	global_store_dwordx2 v[70:71], v[64:65], off
	v_or_b32_e32 v70, 0x1c00, v128
	v_mov_b32_e32 v71, v129
	v_cvt_pk_bf16_f32 v64, v72, v73
	v_cvt_pk_bf16_f32 v65, v74, v75
	v_lshl_add_u64 v[72:73], v[142:143], 0, v[70:71]
	global_store_dwordx2 v[72:73], v[64:65], off
	v_or_b32_e32 v72, 0x1e00, v128
	v_mov_b32_e32 v73, v129
	v_cvt_pk_bf16_f32 v64, v76, v77
	v_cvt_pk_bf16_f32 v65, v78, v79
	v_lshl_add_u64 v[74:75], v[142:143], 0, v[72:73]
	v_or_b32_e32 v98, 0x800, v128
	v_mov_b32_e32 v99, v129
	global_store_dwordx2 v[74:75], v[64:65], off
	v_lshl_add_u64 v[64:65], v[142:143], 0, s[14:15]
	global_store_dwordx2 v[114:115], v[112:113], off
	v_cvt_pk_bf16_f32 v112, v116, v117
	v_or_b32_e32 v116, 0x200, v128
	v_mov_b32_e32 v117, v129
	v_or_b32_e32 v100, 0xa00, v128
	v_mov_b32_e32 v101, v129
	v_cvt_pk_bf16_f32 v48, v48, v49
	v_cvt_pk_bf16_f32 v49, v50, v51
	v_lshl_add_u64 v[50:51], v[64:65], 0, v[128:129]
	v_cvt_pk_bf16_f32 v32, v32, v33
	v_cvt_pk_bf16_f32 v33, v34, v35
	v_lshl_add_u64 v[34:35], v[64:65], 0, v[98:99]
	v_cvt_pk_bf16_f32 v16, v16, v17
	v_cvt_pk_bf16_f32 v17, v18, v19
	v_lshl_add_u64 v[18:19], v[64:65], 0, v[82:83]
	v_cvt_pk_bf16_f32 v0, v0, v1
	v_cvt_pk_bf16_f32 v1, v2, v3
	v_lshl_add_u64 v[2:3], v[64:65], 0, v[66:67]
	v_cvt_pk_bf16_f32 v113, v118, v119
	v_or_b32_e32 v118, 0x400, v128
	v_mov_b32_e32 v119, v129
	v_or_b32_e32 v102, 0xc00, v128
	v_mov_b32_e32 v103, v129
	global_store_dwordx2 v[50:51], v[48:49], off
	v_cvt_pk_bf16_f32 v48, v52, v53
	v_cvt_pk_bf16_f32 v49, v54, v55
	v_lshl_add_u64 v[50:51], v[64:65], 0, v[116:117]
	global_store_dwordx2 v[34:35], v[32:33], off
	v_cvt_pk_bf16_f32 v32, v36, v37
	v_cvt_pk_bf16_f32 v33, v38, v39
	v_lshl_add_u64 v[34:35], v[64:65], 0, v[100:101]
	global_store_dwordx2 v[18:19], v[16:17], off
	v_cvt_pk_bf16_f32 v16, v20, v21
	v_cvt_pk_bf16_f32 v17, v22, v23
	v_lshl_add_u64 v[18:19], v[64:65], 0, v[84:85]
	global_store_dwordx2 v[2:3], v[0:1], off
	v_cvt_pk_bf16_f32 v0, v4, v5
	v_cvt_pk_bf16_f32 v1, v6, v7
	v_lshl_add_u64 v[2:3], v[64:65], 0, v[68:69]
	global_store_dwordx2 v[114:115], v[112:113], off offset:512
	v_cvt_pk_bf16_f32 v112, v120, v121
	v_cvt_pk_bf16_f32 v113, v122, v123
	v_or_b32_e32 v120, 0x600, v128
	v_mov_b32_e32 v121, v129
	v_or_b32_e32 v104, 0xe00, v128
	v_mov_b32_e32 v105, v129
	global_store_dwordx2 v[50:51], v[48:49], off
	v_cvt_pk_bf16_f32 v48, v56, v57
	v_cvt_pk_bf16_f32 v49, v58, v59
	v_lshl_add_u64 v[50:51], v[64:65], 0, v[118:119]
	global_store_dwordx2 v[34:35], v[32:33], off
	v_cvt_pk_bf16_f32 v32, v40, v41
	v_cvt_pk_bf16_f32 v33, v42, v43
	v_lshl_add_u64 v[34:35], v[64:65], 0, v[102:103]
	global_store_dwordx2 v[18:19], v[16:17], off
	v_cvt_pk_bf16_f32 v16, v24, v25
	v_cvt_pk_bf16_f32 v17, v26, v27
	v_lshl_add_u64 v[18:19], v[64:65], 0, v[86:87]
	global_store_dwordx2 v[2:3], v[0:1], off
	v_cvt_pk_bf16_f32 v0, v8, v9
	v_cvt_pk_bf16_f32 v1, v10, v11
	v_lshl_add_u64 v[2:3], v[64:65], 0, v[70:71]
	s_add_i32 s0, s83, 0x100
	global_store_dwordx2 v[114:115], v[112:113], off offset:1024
	v_cvt_pk_bf16_f32 v112, v124, v125
	v_cvt_pk_bf16_f32 v113, v126, v127
	global_store_dwordx2 v[50:51], v[48:49], off
	v_cvt_pk_bf16_f32 v48, v60, v61
	v_cvt_pk_bf16_f32 v49, v62, v63
	v_lshl_add_u64 v[50:51], v[64:65], 0, v[120:121]
	global_store_dwordx2 v[34:35], v[32:33], off
	v_cvt_pk_bf16_f32 v32, v44, v45
	v_cvt_pk_bf16_f32 v33, v46, v47
	v_lshl_add_u64 v[34:35], v[64:65], 0, v[104:105]
	global_store_dwordx2 v[18:19], v[16:17], off
	v_cvt_pk_bf16_f32 v16, v28, v29
	v_cvt_pk_bf16_f32 v17, v30, v31
	v_lshl_add_u64 v[18:19], v[64:65], 0, v[88:89]
	global_store_dwordx2 v[2:3], v[0:1], off
	v_cvt_pk_bf16_f32 v0, v12, v13
	v_cvt_pk_bf16_f32 v1, v14, v15
	v_lshl_add_u64 v[2:3], v[64:65], 0, v[72:73]
	s_cmpk_lt_i32 s83, 0x100
	s_mov_b32 s83, s0
	global_store_dwordx2 v[114:115], v[112:113], off offset:1536
	global_store_dwordx2 v[50:51], v[48:49], off
	global_store_dwordx2 v[34:35], v[32:33], off
	global_store_dwordx2 v[18:19], v[16:17], off
	global_store_dwordx2 v[2:3], v[0:1], off
	s_barrier
; __device__ __forceinline__ unsigned xb_ld(unsigned* p)              { return __hip_atomic_load(p, __ATOMIC_RELAXED, __HIP_MEMORY_SCOPE_AGENT); }
; __device__ __forceinline__ bool xb_thread0(int wave) { return wave == 0 && hw_lane() == 0; }
; __device__ __forceinline__ void xcd_barrier_complete(unsigned* bar, unsigned x, unsigned& nloc, unsigned& nx) {
;     const unsigned G = gridDim.x * gridDim.y * gridDim.z;
;     unsigned sum, cnt, mine, sp = 0u;
;     for (;;) {
;         sum = 0u; cnt = 0u; mine = 0u;
; #pragma unroll
;         for (unsigned j = 0; j < 16; ++j) { const unsigned c = xb_ld(&bar[XB_XCNT(j)]); sum += c; cnt += (c > 0u) ? 1u : 0u; mine = (j == x) ? c : mine; }
;         if (sum == G) break;
;         __builtin_amdgcn_s_sleep(1);
;         if ((++sp & 255u) == 0u) { if (xb_ld(&bar[XB_TMO])) break; if (sp > XB_SPIN_CAP) { atomicAdd(&bar[XB_TMO], 1u); break; } }
;     }
;     nloc = mine > 0u ? mine : 1u; nx = cnt > 0u ? cnt : 1u;
; }
; __device__ __forceinline__ void xcd_barrier_arrive(const XcdBarrier& b) {
;     asm volatile("s_waitcnt vmcnt(0)" ::: "memory");
;     __syncthreads();
;     if (xb_thread0(b.wave)) {
;         unsigned* bar = b.bar;
;         __builtin_amdgcn_s_waitcnt(0);
;         unsigned nloc = b.st[0], nx = b.st[1];
;         if (nloc == 0u) { xcd_barrier_complete(bar, b.x, nloc, nx); b.st[0] = nloc; b.st[1] = nx; }
.LBB0_580:
	v_readlane_b32 s2, v252, 11
	s_waitcnt vmcnt(0)
	v_readlane_b32 s3, v252, 12
	s_andn2_b64 vcc, exec, s[2:3]
	v_readlane_b32 s28, v252, 13
	v_cndmask_b32_e64 v0, 0, 1, s[2:3]
	v_cmp_ne_u32_e64 s[0:1], 1, v0
	s_waitcnt lgkmcnt(0)
	s_barrier
	s_cbranch_vccnz .LBB0_609
	v_mbcnt_lo_u32_b32 v0, -1, 0
	v_mbcnt_hi_u32_b32 v0, -1, v0
	s_nop 0
	v_cmp_eq_u32_e32 vcc, 0, v0
	s_and_saveexec_b64 s[2:3], vcc
	s_cbranch_execz .LBB0_608
	s_add_i32 s4, 0, 0x24160
	v_mov_b32_e32 v0, s4
	s_waitcnt vmcnt(0) expcnt(0) lgkmcnt(0)
	ds_read_b32 v2, v0
	s_add_i32 s4, 0, 0x24164
	v_mov_b32_e32 v0, s4
	ds_read_b32 v0, v0
	s_waitcnt lgkmcnt(1)
	v_cmp_ne_u32_e32 vcc, 0, v2
	s_cbranch_vccnz .LBB0_597
	v_readlane_b32 s6, v252, 0
	v_readlane_b32 s7, v252, 1
	s_load_dwordx2 s[4:5], s[6:7], 0x4
	s_mov_b32 s12, 1
	v_mov_b32_e32 v16, 0
	s_waitcnt lgkmcnt(0)
	s_mul_i32 s4, s4, s5
	s_lshl_b32 s13, s4, 8
	s_add_u32 s4, s66, 0x1000
	s_addc_u32 s5, s67, 0
	s_add_u32 s6, s66, 0x1100
	s_addc_u32 s7, s67, 0
	s_add_u32 s10, s66, 0x1200
	s_addc_u32 s11, s67, 0
	s_add_u32 s14, s66, 0x1300
	s_addc_u32 s15, s67, 0
	s_branch .LBB0_585
